# a21 + mla_prep: AQ/AK/AV rows staged per wave in LDS and written with coalesced 1 KB stores (were 32 row-per-lane stores per thread); vmcnt waits re-derived
# speedup vs baseline: 1.0195x; 1.0132x over previous
.LBB0_535:
	v_ashrrev_i32_e32 v111, 31, v110
	v_lshlrev_b64 v[0:1], 9, v[110:111]
	v_lshl_add_u64 v[0:1], v[106:107], 0, v[0:1]
	global_load_dwordx4 v[24:27], v[0:1], off
	global_load_dwordx4 v[28:31], v[0:1], off offset:16
	global_load_dwordx4 v[36:39], v[0:1], off offset:32
	global_load_dwordx4 v[40:43], v[0:1], off offset:48
	v_ashrrev_i32_e32 v2, 10, v110
	v_and_or_b32 v60, v2, -8, v218
	v_lshlrev_b64 v[2:3], 8, v[110:111]
	v_mad_i64_i32 v[0:1], s[8:9], v110, s18, v[102:103]
	v_lshl_add_u64 v[2:3], v[108:109], 0, v[2:3]
	global_load_dwordx4 v[52:55], v[0:1], off offset:16
	global_load_dwordx4 v[56:59], v[0:1], off
	global_load_dwordx4 v[4:7], v[0:1], off offset:32
	global_load_dwordx4 v[62:65], v[0:1], off offset:48
	global_load_dwordx4 v[8:11], v[0:1], off offset:112
	global_load_dwordx4 v[16:19], v[0:1], off offset:96
	global_load_dwordx4 v[32:35], v[0:1], off offset:80
	global_load_dwordx4 v[48:51], v[0:1], off offset:64
	global_load_dwordx4 v[12:15], v[0:1], off offset:176
	global_load_dwordx4 v[20:23], v[0:1], off offset:160
	global_load_dwordx4 v[66:69], v[2:3], off
	global_load_dwordx4 v[70:73], v[2:3], off offset:16
	global_load_dwordx4 v[44:47], v[0:1], off offset:144
	s_nop 0
	global_load_dwordx4 v[0:3], v[0:1], off offset:128
	v_ashrrev_i32_e32 v61, 31, v60
	v_lshlrev_b64 v[116:117], 13, v[60:61]
	v_and_or_b32 v116, v110, s17, v116
	v_lshlrev_b64 v[80:81], 6, v[110:111]
	v_lshl_add_u64 v[120:121], s[38:39], 0, v[80:81]
	v_lshl_add_u64 v[118:119], s[22:23], 0, v[80:81]
	s_add_i32 s40, s40, s28
	s_cmpk_lt_i32 s40, 0x100
	s_waitcnt vmcnt(17)
	v_and_b32_e32 v61, 0xffff0000, v25
	s_waitcnt vmcnt(16)
	v_lshlrev_b32_e32 v77, 16, v29
	v_lshlrev_b32_e32 v76, 16, v28
	v_and_b32_e32 v29, 0xffff0000, v29
	v_and_b32_e32 v28, 0xffff0000, v28
	s_waitcnt vmcnt(15)
	v_lshlrev_b32_e32 v82, 16, v36
	v_and_b32_e32 v83, 0xffff0000, v36
	v_lshlrev_b32_e32 v36, 16, v37
	v_and_b32_e32 v37, 0xffff0000, v37
	s_waitcnt vmcnt(14)
	v_lshlrev_b32_e32 v90, 16, v41
	v_and_b32_e32 v91, 0xffff0000, v41
	v_lshlrev_b32_e32 v41, 16, v43
	v_lshlrev_b32_e32 v85, 16, v40
	v_and_b32_e32 v87, 0xffff0000, v40
	v_pk_mov_b32 v[88:89], v[38:39], v[42:43] op_sel:[1,0]
	v_pk_mul_f32 v[28:29], v[28:29], v[28:29]
	v_mul_f32_e32 v93, v90, v90
	v_mul_f32_e32 v91, v91, v91
	v_mul_f32_e32 v40, v83, v83
	v_mul_f32_e32 v90, v37, v37
	v_lshlrev_b32_e32 v60, 16, v25
	v_lshlrev_b32_e32 v75, 16, v24
	v_and_b32_e32 v25, 0xffff0000, v24
	v_and_b32_e32 v24, 0xffff0000, v26
	v_and_b32_e32 v92, 0xffff0000, v43
	v_lshlrev_b32_e32 v84, 16, v38
	v_and_b32_e32 v86, 0xffff0000, v38
	v_lshlrev_b32_e32 v43, 16, v42
	v_lshlrev_b32_e32 v42, 16, v39
	v_mul_f32_e32 v38, v61, v61
	v_and_b32_e32 v39, 0xffff0000, v89
	v_pk_fma_f32 v[28:29], v[76:77], v[76:77], v[28:29]
	v_pk_fma_f32 v[76:77], v[82:83], v[82:83], v[40:41] op_sel_hi:[1,1,0]
	v_pk_fma_f32 v[36:37], v[36:37], v[36:37], v[90:91] op_sel_hi:[1,1,0]
	v_lshlrev_b32_e32 v74, 16, v26
	v_pk_mul_f32 v[24:25], v[24:25], v[24:25]
	v_pk_mul_f32 v[86:87], v[86:87], v[86:87]
	v_pk_fma_f32 v[60:61], v[60:61], v[60:61], v[38:39] op_sel_hi:[1,1,0]
	v_mov_b32_e32 v77, v93
	v_mov_b32_e32 v37, v91
	v_and_b32_e32 v38, 0xffff0000, v88
	v_pk_fma_f32 v[24:25], v[74:75], v[74:75], v[24:25]
	v_pk_fma_f32 v[74:75], v[84:85], v[84:85], v[86:87]
	v_pk_add_f32 v[36:37], v[76:77], v[36:37]
	v_pk_mul_f32 v[38:39], v[38:39], v[38:39]
	v_lshlrev_b32_e32 v26, 16, v27
	v_and_b32_e32 v27, 0xffff0000, v27
	v_pk_add_f32 v[36:37], v[74:75], v[36:37]
	v_pk_fma_f32 v[38:39], v[42:43], v[42:43], v[38:39]
	v_lshlrev_b32_e32 v79, 16, v31
	v_lshlrev_b32_e32 v78, 16, v30
	v_and_b32_e32 v31, 0xffff0000, v31
	v_and_b32_e32 v30, 0xffff0000, v30
	v_pk_add_f32 v[60:61], v[24:25], v[60:61] op_sel:[1,0] op_sel_hi:[0,1]
	v_pk_add_f32 v[36:37], v[38:39], v[36:37]
	v_mul_f32_e32 v38, v27, v27
	v_pk_mul_f32 v[30:31], v[30:31], v[30:31]
	v_pk_add_f32 v[24:25], v[24:25], v[60:61]
	v_pk_fma_f32 v[26:27], v[26:27], v[26:27], v[38:39] op_sel_hi:[1,1,0]
	v_pk_fma_f32 v[30:31], v[78:79], v[78:79], v[30:31]
	v_pk_add_f32 v[28:29], v[28:29], v[28:29] op_sel:[0,1] op_sel_hi:[1,0]
	v_mov_b32_e32 v40, v26
	v_mov_b32_e32 v38, v24
	v_mov_b32_e32 v39, v41
	v_pk_add_f32 v[28:29], v[30:31], v[28:29]
	v_pk_add_f32 v[24:25], v[26:27], v[24:25]
	v_pk_mul_f32 v[26:27], v[40:41], v[38:39]
	v_mul_f32_e32 v92, v92, v92
	v_mov_b32_e32 v25, v27
	v_pk_add_f32 v[26:27], v[30:31], v[28:29] op_sel:[1,0] op_sel_hi:[0,1]
	v_mov_b32_e32 v27, v92
	v_pk_add_f32 v[24:25], v[24:25], v[26:27]
	s_waitcnt vmcnt(2)
	v_and_b32_e32 v27, 0xffff0000, v70
	v_pk_add_f32 v[24:25], v[24:25], v[36:37]
	v_and_b32_e32 v26, 0xffff0000, v66
	v_add_f32_e32 v30, v24, v25
	v_lshlrev_b32_e32 v25, 16, v70
	v_lshlrev_b32_e32 v24, 16, v66
	v_pk_mul_f32 v[26:27], v[26:27], v[26:27]
	v_and_b32_e32 v29, 0xffff0000, v71
	v_and_b32_e32 v28, 0xffff0000, v67
	v_pk_fma_f32 v[24:25], v[24:25], v[24:25], v[26:27]
	v_lshlrev_b32_e32 v27, 16, v71
	v_lshlrev_b32_e32 v26, 16, v67
	v_pk_mul_f32 v[28:29], v[28:29], v[28:29]
	v_and_b32_e32 v161, 0xffff0000, v52
	v_pk_fma_f32 v[26:27], v[26:27], v[26:27], v[28:29]
	v_and_b32_e32 v29, 0xffff0000, v72
	v_and_b32_e32 v28, 0xffff0000, v68
	v_pk_add_f32 v[24:25], v[24:25], v[26:27]
	v_lshlrev_b32_e32 v27, 16, v72
	v_lshlrev_b32_e32 v26, 16, v68
	v_pk_mul_f32 v[28:29], v[28:29], v[28:29]
	v_lshlrev_b32_e32 v160, 16, v52
	v_pk_fma_f32 v[26:27], v[26:27], v[26:27], v[28:29]
	v_and_b32_e32 v29, 0xffff0000, v73
	v_and_b32_e32 v28, 0xffff0000, v69
	v_pk_add_f32 v[24:25], v[26:27], v[24:25]
	v_lshlrev_b32_e32 v27, 16, v73
	v_lshlrev_b32_e32 v26, 16, v69
	v_pk_mul_f32 v[28:29], v[28:29], v[28:29]
	v_and_b32_e32 v163, 0xffff0000, v53
	v_pk_fma_f32 v[26:27], v[26:27], v[26:27], v[28:29]
	v_lshlrev_b32_e32 v162, 16, v53
	v_pk_add_f32 v[24:25], v[26:27], v[24:25]
	v_and_b32_e32 v85, 0xffff0000, v63
	v_add_f32_e32 v28, v24, v25
	v_mul_f32_e32 v24, v161, v161
	v_pk_fma_f32 v[60:61], v[160:161], v[160:161], v[24:25] op_sel_hi:[1,1,0]
	v_mul_f32_e32 v24, v163, v163
	v_and_b32_e32 v84, 0xffff0000, v62
	ds_swizzle_b32 v29, v30 offset:swizzle(SWAP,1)
	v_pk_fma_f32 v[52:53], v[162:163], v[162:163], v[24:25] op_sel_hi:[1,1,0]
	v_lshlrev_b32_e32 v123, 16, v63
	v_lshlrev_b32_e32 v122, 16, v62
	v_pk_mul_f32 v[24:25], v[84:85], v[84:85]
	v_and_b32_e32 v87, 0xffff0000, v65
	v_and_b32_e32 v86, 0xffff0000, v64
	v_pk_fma_f32 v[24:25], v[122:123], v[122:123], v[24:25]
	v_lshlrev_b32_e32 v129, 16, v65
	v_lshlrev_b32_e32 v128, 16, v64
	v_pk_mul_f32 v[26:27], v[86:87], v[86:87]
	v_pk_add_f32 v[24:25], v[24:25], v[24:25] op_sel:[0,1] op_sel_hi:[1,0]
	v_pk_fma_f32 v[26:27], v[128:129], v[128:129], v[26:27]
	v_and_b32_e32 v167, 0xffff0000, v48
	v_pk_add_f32 v[24:25], v[26:27], v[24:25]
	v_lshlrev_b32_e32 v166, 16, v48
	v_pk_add_f32 v[184:185], v[26:27], v[24:25] op_sel:[1,0] op_sel_hi:[0,1]
	s_waitcnt lgkmcnt(0)
	v_add_f32_e32 v25, v30, v29
	ds_swizzle_b32 v26, v25 offset:swizzle(SWAP,2)
	v_mul_f32_e32 v24, v167, v167
	v_pk_fma_f32 v[72:73], v[166:167], v[166:167], v[24:25] op_sel_hi:[1,1,0]
	v_and_b32_e32 v191, 0xffff0000, v58
	v_and_b32_e32 v195, 0xffff0000, v56
	s_waitcnt lgkmcnt(0)
	v_add_f32_e32 v25, v25, v26
	ds_swizzle_b32 v26, v25 offset:swizzle(SWAP,4)
	v_lshlrev_b32_e32 v188, 16, v59
	v_and_b32_e32 v189, 0xffff0000, v59
	v_lshlrev_b32_e32 v190, 16, v58
	v_and_b32_e32 v193, 0xffff0000, v57
	v_lshlrev_b32_e32 v194, 16, v56
	v_mov_b32_e32 v58, v191
	v_mov_b32_e32 v59, v195
	v_lshlrev_b32_e32 v192, 16, v57
	v_mul_f32_e32 v48, v193, v193
	v_mov_b32_e32 v56, v190
	v_mov_b32_e32 v57, v194
	v_pk_mul_f32 v[58:59], v[58:59], v[58:59]
	v_lshlrev_b32_e32 v170, 16, v49
	ds_swizzle_b32 v27, v28 offset:swizzle(SWAP,1)
	v_and_b32_e32 v171, 0xffff0000, v49
	v_pk_fma_f32 v[48:49], v[192:193], v[192:193], v[48:49] op_sel_hi:[1,1,0]
	v_pk_fma_f32 v[56:57], v[56:57], v[56:57], v[58:59]
	v_and_b32_e32 v155, 0xffff0000, v4
	v_pk_add_f32 v[48:49], v[56:57], v[48:49] op_sel:[1,0] op_sel_hi:[0,1]
	v_and_b32_e32 v154, 0xffff0000, v54
	v_mul_f32_e32 v24, v171, v171
	v_pk_add_f32 v[56:57], v[56:57], v[48:49]
	v_lshlrev_b32_e32 v159, 16, v4
	v_lshlrev_b32_e32 v158, 16, v54
	v_pk_mul_f32 v[48:49], v[154:155], v[154:155]
	v_pk_fma_f32 v[76:77], v[170:171], v[170:171], v[24:25] op_sel_hi:[1,1,0]
	s_waitcnt lgkmcnt(1)
	v_add_f32_e32 v24, v25, v26
	v_pk_fma_f32 v[58:59], v[158:159], v[158:159], v[48:49]
	v_pk_mov_b32 v[48:49], v[54:55], v[6:7] op_sel:[1,0]
	v_fmamk_f32 v24, v24, 0x3b800000, v100
	v_and_b32_e32 v157, 0xffff0000, v49
	v_and_b32_e32 v156, 0xffff0000, v48
	s_waitcnt lgkmcnt(0)
	v_add_f32_e32 v25, v28, v27
	v_mul_f32_e32 v27, 0x4b800000, v24
	v_cmp_gt_f32_e32 vcc, s19, v24
	v_lshlrev_b32_e32 v173, 16, v6
	v_lshlrev_b32_e32 v172, 16, v55
	v_pk_mul_f32 v[48:49], v[156:157], v[156:157]
	s_waitcnt vmcnt(0)
	v_and_b32_e32 v145, 0xffff0000, v0
	v_and_b32_e32 v144, 0xffff0000, v50
	ds_swizzle_b32 v26, v25 offset:swizzle(SWAP,2)
	v_cndmask_b32_e32 v24, v24, v27, vcc
	v_pk_fma_f32 v[54:55], v[172:173], v[172:173], v[48:49]
	v_lshlrev_b32_e32 v143, 16, v0
	v_lshlrev_b32_e32 v142, 16, v50
	v_pk_mul_f32 v[48:49], v[144:145], v[144:145]
	v_rsq_f32_e32 v24, v24
	v_pk_fma_f32 v[202:203], v[142:143], v[142:143], v[48:49]
	v_pk_mov_b32 v[48:49], v[50:51], v[2:3] op_sel:[1,0]
	v_lshlrev_b32_e32 v139, 16, v2
	v_and_b32_e32 v141, 0xffff0000, v49
	v_and_b32_e32 v140, 0xffff0000, v48
	v_lshlrev_b32_e32 v138, 16, v51
	v_pk_mul_f32 v[48:49], v[140:141], v[140:141]
	v_and_b32_e32 v99, 0xffff0000, v44
	v_and_b32_e32 v98, 0xffff0000, v32
	v_and_b32_e32 v91, 0xffff0000, v45
	v_and_b32_e32 v90, 0xffff0000, v33
	v_pk_fma_f32 v[204:205], v[138:139], v[138:139], v[48:49]
	v_lshlrev_b32_e32 v97, 16, v44
	v_lshlrev_b32_e32 v96, 16, v32
	v_pk_mul_f32 v[48:49], v[98:99], v[98:99]
	v_lshlrev_b32_e32 v89, 16, v45
	v_lshlrev_b32_e32 v88, 16, v33
	v_pk_mul_f32 v[32:33], v[90:91], v[90:91]
	v_and_b32_e32 v127, 0xffff0000, v46
	v_and_b32_e32 v126, 0xffff0000, v34
	s_waitcnt lgkmcnt(0)
	v_add_f32_e32 v75, v25, v26
	v_mul_f32_e32 v25, 0x45800000, v24
	v_pk_fma_f32 v[48:49], v[96:97], v[96:97], v[48:49]
	v_pk_fma_f32 v[32:33], v[88:89], v[88:89], v[32:33]
	v_lshlrev_b32_e32 v125, 16, v46
	v_lshlrev_b32_e32 v124, 16, v34
	v_pk_mul_f32 v[44:45], v[126:127], v[126:127]
	v_and_b32_e32 v95, 0xffff0000, v47
	v_and_b32_e32 v94, 0xffff0000, v35
	v_cndmask_b32_e32 v219, v24, v25, vcc
	global_load_dwordx4 v[24:27], v101, s[44:45] offset:48
	global_load_dwordx4 v[28:31], v101, s[44:45] offset:32
	global_load_dwordx4 v[36:39], v101, s[44:45] offset:16
	global_load_dwordx4 v[40:43], v101, s[44:45]
	v_pk_add_f32 v[32:33], v[48:49], v[32:33]
	v_pk_fma_f32 v[44:45], v[124:125], v[124:125], v[44:45]
	v_lshlrev_b32_e32 v93, 16, v47
	v_lshlrev_b32_e32 v92, 16, v35
	v_pk_mul_f32 v[34:35], v[94:95], v[94:95]
	v_pk_add_f32 v[32:33], v[44:45], v[32:33]
	v_pk_fma_f32 v[34:35], v[92:93], v[92:93], v[34:35]
	v_and_b32_e32 v179, 0xffff0000, v20
	v_and_b32_e32 v178, 0xffff0000, v16
	v_and_b32_e32 v169, 0xffff0000, v21
	v_and_b32_e32 v168, 0xffff0000, v17
	v_pk_add_f32 v[32:33], v[34:35], v[32:33]
	v_lshlrev_b32_e32 v177, 16, v20
	v_lshlrev_b32_e32 v176, 16, v16
	v_pk_mul_f32 v[34:35], v[178:179], v[178:179]
	v_lshlrev_b32_e32 v165, 16, v21
	v_lshlrev_b32_e32 v164, 16, v17
	v_pk_mul_f32 v[16:17], v[168:169], v[168:169]
	v_and_b32_e32 v183, 0xffff0000, v22
	v_and_b32_e32 v182, 0xffff0000, v18
	v_pk_fma_f32 v[34:35], v[176:177], v[176:177], v[34:35]
	v_pk_fma_f32 v[16:17], v[164:165], v[164:165], v[16:17]
	v_lshlrev_b32_e32 v181, 16, v22
	v_lshlrev_b32_e32 v180, 16, v18
	v_pk_mul_f32 v[20:21], v[182:183], v[182:183]
	v_and_b32_e32 v175, 0xffff0000, v23
	v_and_b32_e32 v174, 0xffff0000, v19
	v_pk_add_f32 v[16:17], v[34:35], v[16:17]
	v_pk_fma_f32 v[20:21], v[180:181], v[180:181], v[20:21]
	v_lshlrev_b32_e32 v187, 16, v23
	v_lshlrev_b32_e32 v186, 16, v19
	v_pk_mul_f32 v[18:19], v[174:175], v[174:175]
	v_pk_add_f32 v[16:17], v[20:21], v[16:17]
	v_pk_fma_f32 v[18:19], v[186:187], v[186:187], v[18:19]
	v_and_b32_e32 v149, 0xffff0000, v12
	v_and_b32_e32 v148, 0xffff0000, v8
	v_and_b32_e32 v133, 0xffff0000, v13
	v_and_b32_e32 v132, 0xffff0000, v9
	v_pk_add_f32 v[34:35], v[18:19], v[16:17]
	v_lshlrev_b32_e32 v147, 16, v12
	v_lshlrev_b32_e32 v146, 16, v8
	v_pk_mul_f32 v[16:17], v[148:149], v[148:149]
	v_lshlrev_b32_e32 v131, 16, v13
	v_lshlrev_b32_e32 v130, 16, v9
	v_pk_mul_f32 v[8:9], v[132:133], v[132:133]
	v_pk_fma_f32 v[16:17], v[146:147], v[146:147], v[16:17]
	v_pk_fma_f32 v[8:9], v[130:131], v[130:131], v[8:9]
	v_and_b32_e32 v153, 0xffff0000, v14
	v_pk_add_f32 v[8:9], v[16:17], v[8:9]
	global_load_dwordx4 v[16:19], v101, s[44:45] offset:112
	global_load_dwordx4 v[20:23], v101, s[44:45] offset:96
	global_load_dwordx4 v[44:47], v101, s[44:45] offset:80
	global_load_dwordx4 v[48:51], v101, s[44:45] offset:64
	global_load_dwordx4 v[208:211], v101, s[44:45] offset:176
	global_load_dwordx4 v[212:215], v101, s[44:45] offset:160
	global_load_dwordx4 v[220:223], v101, s[44:45] offset:144
	global_load_dwordx4 v[224:227], v101, s[44:45] offset:128
	v_and_b32_e32 v152, 0xffff0000, v10
	v_lshlrev_b32_e32 v151, 16, v14
	v_lshlrev_b32_e32 v150, 16, v10
	v_pk_mul_f32 v[12:13], v[152:153], v[152:153]
	v_and_b32_e32 v137, 0xffff0000, v15
	v_and_b32_e32 v136, 0xffff0000, v11
	v_mul_f32_e32 v62, v189, v189
	v_pk_fma_f32 v[12:13], v[150:151], v[150:151], v[12:13]
	v_lshlrev_b32_e32 v135, 16, v15
	v_lshlrev_b32_e32 v134, 16, v11
	v_pk_mul_f32 v[10:11], v[136:137], v[136:137]
	v_lshlrev_b32_e32 v196, 16, v7
	v_and_b32_e32 v7, 0xffff0000, v7
	v_lshlrev_b32_e32 v198, 16, v5
	v_and_b32_e32 v199, 0xffff0000, v5
	v_mov_b32_e32 v63, v62
	v_pk_add_f32 v[8:9], v[12:13], v[8:9]
	v_pk_fma_f32 v[10:11], v[134:135], v[134:135], v[10:11]
	v_mov_b32_e32 v197, v7
	v_pk_mul_f32 v[4:5], v[198:199], v[198:199]
	v_pk_add_f32 v[216:217], v[10:11], v[8:9]
	v_and_b32_e32 v6, s0, v6
	v_pk_mov_b32 v[8:9], v[62:63], v[196:197] op_sel:[1,0]
	v_mov_b32_e32 v61, v4
	v_mov_b32_e32 v53, v5
	v_pk_mul_f32 v[6:7], v[6:7], v[6:7]
	v_pk_fma_f32 v[10:11], v[188:189], v[188:189], v[8:9]
	v_pk_mul_f32 v[8:9], v[196:197], v[8:9] op_sel_hi:[0,1]
	v_pk_add_f32 v[4:5], v[60:61], v[52:53]
	v_mov_b32_e32 v11, v9
	v_mov_b32_e32 v57, v7
	v_pk_add_f32 v[4:5], v[58:59], v[4:5]
	v_pk_add_f32 v[6:7], v[10:11], v[56:57]
	v_pk_add_f32 v[4:5], v[54:55], v[4:5]
	v_lshlrev_b32_e32 v200, 16, v3
	v_pk_add_f32 v[4:5], v[6:7], v[4:5]
	v_and_b32_e32 v201, 0xffff0000, v3
	v_pk_add_f32 v[206:207], v[4:5], v[4:5] op_sel:[0,1] op_sel_hi:[1,0]
	v_pk_mul_f32 v[2:3], v[200:201], v[200:201]
	ds_swizzle_b32 v79, v75 offset:swizzle(SWAP,4)
	v_mov_b32_e32 v185, v3
	v_mov_b32_e32 v207, v2
	v_pk_add_f32 v[2:3], v[206:207], v[184:185]
	v_lshlrev_b32_e32 v206, 16, v1
	v_and_b32_e32 v207, 0xffff0000, v1
	v_pk_mul_f32 v[0:1], v[206:207], v[206:207]
	v_mul_f32_e32 v74, v219, v219
	v_mov_b32_e32 v73, v0
	v_mov_b32_e32 v77, v1
	v_pk_add_f32 v[0:1], v[72:73], v[76:77]
	v_mov_b32_e32 v240, v88
	v_pk_add_f32 v[0:1], v[202:203], v[0:1]
	v_mov_b32_e32 v241, v90
	v_pk_add_f32 v[0:1], v[204:205], v[0:1]
	v_mad_u64_u32 v[82:83], s[8:9], v116, s35, v[112:113]
	v_pk_add_f32 v[0:1], v[2:3], v[0:1]
	v_mad_i32_i24 v83, v117, s35, v83
	v_pk_add_f32 v[0:1], v[0:1], v[32:33]
	v_mov_b32_e32 v228, v158
	v_pk_add_f32 v[0:1], v[0:1], v[34:35]
	v_mov_b32_e32 v229, v154
	v_pk_add_f32 v[0:1], v[0:1], v[216:217]
	global_load_dwordx4 v[12:15], v101, s[44:45] offset:240
	global_load_dwordx4 v[56:59], v101, s[44:45] offset:224
	global_load_dwordx4 v[64:67], v101, s[44:45] offset:208
	global_load_dwordx4 v[68:71], v101, s[44:45] offset:192
	global_load_dwordx4 v[4:7], v101, s[44:45] offset:304
	global_load_dwordx4 v[8:11], v101, s[44:45] offset:288
	global_load_dwordx4 v[60:63], v101, s[44:45] offset:256
	global_load_dwordx4 v[52:55], v101, s[44:45] offset:272
	v_pk_mul_f32 v[0:1], v[0:1], v[74:75] op_sel_hi:[1,0]
	v_mov_b32_e32 v230, v172
	v_mov_b32_e32 v74, v0
	v_mov_b32_e32 v78, v1
	s_waitcnt lgkmcnt(0)
	v_pk_add_f32 v[0:1], v[74:75], v[78:79]
	v_mov_b32_e32 v231, v156
	v_pk_fma_f32 v[184:185], v[0:1], s[14:15], v[100:101] op_sel_hi:[1,1,0]
	v_mov_b32_e32 v232, v142
	v_mul_f32_e32 v0, 0x4b800000, v184
	v_cmp_gt_f32_e32 vcc, s19, v184
	v_mov_b32_e32 v233, v144
	v_mov_b32_e32 v234, v138
	v_cndmask_b32_e32 v0, v184, v0, vcc
	v_rsq_f32_e32 v88, v0
	global_load_dwordx4 v[0:3], v101, s[44:45] offset:368
	global_load_dwordx4 v[32:35], v101, s[44:45] offset:352
	global_load_dwordx4 v[76:79], v101, s[44:45] offset:320
	global_load_dwordx4 v[72:75], v101, s[44:45] offset:336
	v_mov_b32_e32 v235, v140
	v_mov_b32_e32 v236, v96
	v_mul_f32_e32 v90, 0x45800000, v88
	v_cndmask_b32_e32 v88, v88, v90, vcc
	v_mul_f32_e32 v88, 0x3e16c740, v88
	v_mul_f32_e32 v88, v219, v88
	s_waitcnt vmcnt(21)
	v_pk_mul_f32 v[36:37], v[36:37], v[88:89] op_sel_hi:[1,0]
	s_waitcnt vmcnt(20)
	v_pk_mul_f32 v[40:41], v[40:41], v[88:89] op_sel_hi:[1,0]
	v_pk_mul_f32 v[190:191], v[36:37], v[190:191]
	v_pk_mul_f32 v[36:37], v[42:43], v[88:89] op_sel_hi:[1,0]
	v_pk_mul_f32 v[40:41], v[40:41], v[194:195]
	v_pk_mul_f32 v[42:43], v[36:37], v[192:193]
	v_pk_mul_f32 v[36:37], v[38:39], v[88:89] op_sel_hi:[1,0]
	v_cvt_pk_bf16_f32 v38, v190, v191
	v_pk_mul_f32 v[188:189], v[36:37], v[188:189]
	v_cvt_pk_bf16_f32 v36, v40, v41
	v_cvt_pk_bf16_f32 v37, v42, v43
	v_cvt_pk_bf16_f32 v39, v188, v189
	v_pk_mul_f32 v[24:25], v[24:25], v[88:89] op_sel_hi:[1,0]
	s_mul_i32 s57, s33, 0xc0
	v_mbcnt_lo_u32_b32 v244, -1, 0
	v_mbcnt_hi_u32_b32 v244, -1, v244
	v_mul_u32_u24_e32 v244, 0xc0, v244
	v_add_u32_e32 v244, s57, v244
	ds_write_b128 v244, v[36:39]
	v_pk_mul_f32 v[28:29], v[28:29], v[88:89] op_sel_hi:[1,0]
	v_mov_b32_e32 v237, v98
	v_pk_mul_f32 v[36:37], v[24:25], v[228:229]
	v_pk_mul_f32 v[24:25], v[30:31], v[88:89] op_sel_hi:[1,0]
	v_pk_mul_f32 v[28:29], v[28:29], v[160:161]
	v_pk_mul_f32 v[30:31], v[24:25], v[162:163]
	v_pk_mul_f32 v[24:25], v[26:27], v[88:89] op_sel_hi:[1,0]
	v_cvt_pk_bf16_f32 v26, v36, v37
	v_pk_mul_f32 v[38:39], v[24:25], v[230:231]
	v_cvt_pk_bf16_f32 v24, v28, v29
	v_cvt_pk_bf16_f32 v25, v30, v31
	v_cvt_pk_bf16_f32 v27, v38, v39
	ds_write_b128 v244, v[24:27] offset:16
	s_waitcnt vmcnt(12)
	v_pk_mul_f32 v[28:29], v[226:227], v[88:89] op_sel_hi:[1,0]
	v_pk_mul_f32 v[30:31], v[222:223], v[88:89] op_sel_hi:[1,0]
	v_pk_mul_f32 v[24:25], v[224:225], v[88:89] op_sel_hi:[1,0]
	v_pk_mul_f32 v[26:27], v[220:221], v[88:89] op_sel_hi:[1,0]
	v_pk_mul_f32 v[24:25], v[24:25], v[166:167]
	v_pk_mul_f32 v[26:27], v[26:27], v[232:233]
	v_pk_mul_f32 v[28:29], v[28:29], v[170:171]
	v_pk_mul_f32 v[30:31], v[30:31], v[234:235]
	v_cvt_pk_bf16_f32 v24, v24, v25
	v_cvt_pk_bf16_f32 v25, v28, v29
	v_cvt_pk_bf16_f32 v26, v26, v27
	v_cvt_pk_bf16_f32 v27, v30, v31
	v_mov_b32_e32 v238, v124
	v_mov_b32_e32 v239, v126
	v_mov_b32_e32 v242, v92
	v_mov_b32_e32 v243, v94
	ds_write_b128 v244, v[24:27] offset:64
	v_pk_mul_f32 v[28:29], v[88:89], v[214:215] op_sel_hi:[0,1]
	v_pk_mul_f32 v[30:31], v[88:89], v[210:211] op_sel_hi:[0,1]
	v_pk_mul_f32 v[24:25], v[88:89], v[212:213] op_sel_hi:[0,1]
	v_pk_mul_f32 v[26:27], v[88:89], v[208:209] op_sel_hi:[0,1]
	v_pk_mul_f32 v[24:25], v[24:25], v[236:237]
	v_pk_mul_f32 v[26:27], v[26:27], v[238:239]
	v_pk_mul_f32 v[28:29], v[28:29], v[240:241]
	v_pk_mul_f32 v[30:31], v[30:31], v[242:243]
	v_cvt_pk_bf16_f32 v24, v24, v25
	v_cvt_pk_bf16_f32 v25, v28, v29
	v_cvt_pk_bf16_f32 v26, v26, v27
	v_cvt_pk_bf16_f32 v27, v30, v31
	global_load_dwordx4 v[28:31], v[120:121], off
	global_load_dwordx4 v[36:39], v[118:119], off
	v_mov_b32_e32 v156, v173
	ds_write_b128 v244, v[24:27] offset:80
	global_load_dwordx4 v[24:27], v[118:119], off offset:16
	s_nop 0
	global_load_dwordx4 v[40:43], v[120:121], off offset:16
	v_mov_b32_e32 v154, v159
	v_pk_mul_f32 v[48:49], v[48:49], v[88:89] op_sel_hi:[1,0]
	v_pk_mul_f32 v[44:45], v[44:45], v[88:89] op_sel_hi:[1,0]
	v_pk_mul_f32 v[48:49], v[48:49], v[154:155]
	v_pk_mul_f32 v[154:155], v[44:45], v[156:157]
	v_pk_mul_f32 v[44:45], v[50:51], v[88:89] op_sel_hi:[1,0]
	v_mov_b32_e32 v160, v128
	v_pk_mul_f32 v[50:51], v[44:45], v[198:199]
	v_pk_mul_f32 v[44:45], v[46:47], v[88:89] op_sel_hi:[1,0]
	v_mov_b32_e32 v161, v86
	v_pk_mul_f32 v[156:157], v[44:45], v[196:197]
	v_cvt_pk_bf16_f32 v44, v48, v49
	v_cvt_pk_bf16_f32 v45, v50, v51
	v_cvt_pk_bf16_f32 v46, v154, v155
	v_cvt_pk_bf16_f32 v47, v156, v157
	v_pk_mul_f32 v[16:17], v[16:17], v[88:89] op_sel_hi:[1,0]
	v_mov_b32_e32 v159, v84
	v_mov_b32_e32 v84, v123
	ds_write_b128 v244, v[44:47] offset:32
	v_mov_b32_e32 v158, v122
	v_mov_b32_e32 v86, v129
	v_pk_mul_f32 v[44:45], v[16:17], v[160:161]
	v_pk_mul_f32 v[16:17], v[22:23], v[88:89] op_sel_hi:[1,0]
	v_pk_mul_f32 v[20:21], v[20:21], v[88:89] op_sel_hi:[1,0]
	v_pk_mul_f32 v[22:23], v[16:17], v[84:85]
	v_pk_mul_f32 v[16:17], v[18:19], v[88:89] op_sel_hi:[1,0]
	v_pk_mul_f32 v[20:21], v[20:21], v[158:159]
	v_pk_mul_f32 v[46:47], v[16:17], v[86:87]
	v_cvt_pk_bf16_f32 v16, v20, v21
	v_cvt_pk_bf16_f32 v17, v22, v23
	v_cvt_pk_bf16_f32 v18, v44, v45
	v_cvt_pk_bf16_f32 v19, v46, v47
	v_mov_b32_e32 v122, v176
	v_mov_b32_e32 v123, v178
	v_mov_b32_e32 v128, v180
	v_mov_b32_e32 v129, v182
	v_mov_b32_e32 v162, v164
	v_mov_b32_e32 v163, v168
	v_mov_b32_e32 v166, v186
	v_mov_b32_e32 v167, v174
	ds_write_b128 v244, v[16:19] offset:48
	s_waitcnt vmcnt(12)
	v_pk_mul_f32 v[20:21], v[88:89], v[70:71] op_sel_hi:[0,1]
	v_pk_mul_f32 v[22:23], v[88:89], v[66:67] op_sel_hi:[0,1]
	v_pk_mul_f32 v[16:17], v[88:89], v[68:69] op_sel_hi:[0,1]
	v_pk_mul_f32 v[18:19], v[88:89], v[64:65] op_sel_hi:[0,1]
	v_pk_mul_f32 v[16:17], v[16:17], v[122:123]
	v_pk_mul_f32 v[18:19], v[18:19], v[128:129]
	v_pk_mul_f32 v[20:21], v[20:21], v[162:163]
	v_pk_mul_f32 v[22:23], v[22:23], v[166:167]
	v_cvt_pk_bf16_f32 v16, v16, v17
	v_cvt_pk_bf16_f32 v17, v20, v21
	v_cvt_pk_bf16_f32 v18, v18, v19
	v_cvt_pk_bf16_f32 v19, v22, v23
	v_mov_b32_e32 v182, v181
	v_mov_b32_e32 v170, v146
	v_mov_b32_e32 v171, v148
	ds_write_b128 v244, v[16:19] offset:96
	v_mov_b32_e32 v144, v143
	v_mov_b32_e32 v140, v139
	v_pk_mul_f32 v[16:17], v[88:89], v[56:57] op_sel_hi:[0,1]
	v_pk_mul_f32 v[18:19], v[88:89], v[182:183] op_sel_hi:[0,1]
	v_mov_b32_e32 v172, v150
	v_mov_b32_e32 v173, v152
	v_mov_b32_e32 v174, v187
	v_pk_mul_f32 v[44:45], v[16:17], v[170:171]
	v_pk_mul_f32 v[12:13], v[88:89], v[12:13] op_sel_hi:[0,1]
	v_pk_mul_f32 v[16:17], v[88:89], v[144:145] op_sel_hi:[0,1]
	v_mov_b32_e32 v178, v177
	s_waitcnt vmcnt(4)
	v_pk_mul_f32 v[56:57], v[18:19], v[72:73]
	v_pk_mul_f32 v[18:19], v[88:89], v[140:141] op_sel_hi:[0,1]
	v_pk_mul_f32 v[20:21], v[88:89], v[206:207] op_sel_hi:[0,1]
	v_mov_b32_e32 v168, v165
	v_pk_mul_f32 v[22:23], v[88:89], v[200:201] op_sel_hi:[0,1]
	v_pk_mul_f32 v[46:47], v[12:13], v[172:173]
	v_pk_mul_f32 v[12:13], v[88:89], v[58:59] op_sel_hi:[0,1]
	v_pk_mul_f32 v[48:49], v[16:17], v[60:61]
	v_pk_mul_f32 v[16:17], v[88:89], v[178:179] op_sel_hi:[0,1]
	v_pk_mul_f32 v[52:53], v[18:19], v[52:53]
	v_pk_mul_f32 v[58:59], v[20:21], v[62:63]
	v_pk_mul_f32 v[20:21], v[88:89], v[168:169] op_sel_hi:[0,1]
	v_pk_mul_f32 v[54:55], v[22:23], v[54:55]
	v_pk_mul_f32 v[22:23], v[88:89], v[174:175] op_sel_hi:[0,1]
	v_pk_mul_f32 v[50:51], v[16:17], v[76:77]
	s_waitcnt vmcnt(3)
	v_pk_mul_f32 v[16:17], v[48:49], v[28:29]
	s_waitcnt vmcnt(0)
	v_pk_mul_f32 v[18:19], v[52:53], v[40:41]
	v_pk_mul_f32 v[60:61], v[20:21], v[78:79]
	v_pk_mul_f32 v[20:21], v[58:59], v[30:31]
	v_pk_mul_f32 v[62:63], v[22:23], v[74:75]
	v_pk_mul_f32 v[22:23], v[54:55], v[42:43]
	v_pk_fma_f32 v[16:17], v[50:51], v[36:37], v[16:17]
	v_pk_fma_f32 v[18:19], v[56:57], v[24:25], v[18:19]
	v_pk_fma_f32 v[20:21], v[60:61], v[38:39], v[20:21]
	v_pk_fma_f32 v[22:23], v[62:63], v[26:27], v[22:23]
	v_mov_b32_e32 v188, v130
	v_mov_b32_e32 v189, v132
	v_cvt_pk_bf16_f32 v16, v16, v17
	v_cvt_pk_bf16_f32 v17, v20, v21
	v_cvt_pk_bf16_f32 v18, v18, v19
	v_cvt_pk_bf16_f32 v19, v22, v23
	v_mov_b32_e32 v190, v134
	v_mov_b32_e32 v191, v136
	ds_write_b128 v244, v[16:19] offset:160
	v_pk_mul_f32 v[64:65], v[12:13], v[188:189]
	v_pk_mul_f32 v[12:13], v[88:89], v[14:15] op_sel_hi:[0,1]
	global_load_dwordx4 v[16:19], v[120:121], off offset:32
	global_load_dwordx4 v[20:23], v[118:119], off offset:32
	v_pk_mul_f32 v[66:67], v[12:13], v[190:191]
	v_cvt_pk_bf16_f32 v12, v44, v45
	v_cvt_pk_bf16_f32 v13, v64, v65
	v_cvt_pk_bf16_f32 v14, v46, v47
	v_cvt_pk_bf16_f32 v15, v66, v67
	ds_write_b128 v244, v[12:15] offset:112
	global_load_dwordx4 v[12:15], v[120:121], off offset:48
	s_nop 0
	global_load_dwordx4 v[44:47], v[118:119], off offset:48
	v_pk_mul_f32 v[28:29], v[50:51], v[28:29]
	v_mov_b32_e32 v98, v97
	v_pk_fma_f32 v[28:29], v[48:49], v[36:37], v[28:29] neg_lo:[0,0,1] neg_hi:[0,0,1]
	v_pk_mul_f32 v[36:37], v[56:57], v[40:41]
	v_mov_b32_e32 v148, v147
	v_pk_fma_f32 v[36:37], v[52:53], v[24:25], v[36:37] neg_lo:[0,0,1] neg_hi:[0,0,1]
	v_pk_mul_f32 v[24:25], v[60:61], v[30:31]
	v_mov_b32_e32 v152, v151
	v_pk_fma_f32 v[30:31], v[58:59], v[38:39], v[24:25] neg_lo:[0,0,1] neg_hi:[0,0,1]
	v_pk_mul_f32 v[24:25], v[62:63], v[42:43]
	v_mov_b32_e32 v126, v125
	v_pk_fma_f32 v[38:39], v[54:55], v[26:27], v[24:25] neg_lo:[0,0,1] neg_hi:[0,0,1]
	v_cvt_pk_bf16_f32 v24, v28, v29
	v_cvt_pk_bf16_f32 v25, v30, v31
	v_cvt_pk_bf16_f32 v26, v36, v37
	v_cvt_pk_bf16_f32 v27, v38, v39
	ds_write_b128 v244, v[24:27] offset:128
	v_mov_b32_e32 v90, v89
	v_mov_b32_e32 v132, v131
	v_pk_mul_f32 v[24:25], v[88:89], v[98:99] op_sel_hi:[0,1]
	v_pk_mul_f32 v[8:9], v[24:25], v[8:9]
	v_pk_mul_f32 v[24:25], v[88:89], v[148:149] op_sel_hi:[0,1]
	v_pk_mul_f32 v[24:25], v[24:25], v[32:33]
	v_mov_b32_e32 v94, v93
	v_mov_b32_e32 v136, v135
	v_lshlrev_b64 v[64:65], 11, v[110:111]
	v_lshl_add_u64 v[64:65], v[104:105], 0, v[64:65]
	v_cmp_gt_f32_e32 vcc, s19, v185
	v_lshl_add_u64 v[40:41], s[20:21], 0, v[80:81]
	v_mad_u64_u32 v[124:125], s[8:9], v116, s35, v[114:115]
	v_mad_i32_i24 v125, v117, s35, v125
	v_add_u32_e32 v110, s16, v110
	s_waitcnt vmcnt(3)
	v_pk_mul_f32 v[26:27], v[8:9], v[16:17]
	v_pk_mul_f32 v[16:17], v[24:25], v[16:17]
	s_waitcnt vmcnt(2)
	v_pk_fma_f32 v[26:27], v[24:25], v[20:21], v[26:27]
	v_pk_fma_f32 v[8:9], v[8:9], v[20:21], v[16:17] neg_lo:[0,0,1] neg_hi:[0,0,1]
	v_pk_mul_f32 v[16:17], v[88:89], v[152:153] op_sel_hi:[0,1]
	v_pk_mul_f32 v[0:1], v[16:17], v[0:1]
	v_pk_mul_f32 v[16:17], v[88:89], v[126:127] op_sel_hi:[0,1]
	v_pk_mul_f32 v[4:5], v[16:17], v[4:5]
	s_waitcnt vmcnt(1)
	v_pk_mul_f32 v[16:17], v[0:1], v[12:13]
	s_waitcnt vmcnt(0)
	v_pk_fma_f32 v[16:17], v[4:5], v[44:45], v[16:17] neg_lo:[0,0,1] neg_hi:[0,0,1]
	v_pk_mul_f32 v[4:5], v[4:5], v[12:13]
	s_nop 0
	v_pk_fma_f32 v[4:5], v[0:1], v[44:45], v[4:5]
	v_pk_mul_f32 v[0:1], v[88:89], v[90:91] op_sel_hi:[0,1]
	v_pk_mul_f32 v[0:1], v[0:1], v[10:11]
	v_pk_mul_f32 v[10:11], v[88:89], v[132:133] op_sel_hi:[0,1]
	v_pk_mul_f32 v[10:11], v[10:11], v[34:35]
	v_pk_mul_f32 v[12:13], v[0:1], v[18:19]
	s_nop 0
	v_pk_fma_f32 v[12:13], v[10:11], v[22:23], v[12:13]
	v_pk_mul_f32 v[10:11], v[10:11], v[18:19]
	s_nop 0
	v_pk_fma_f32 v[10:11], v[0:1], v[22:23], v[10:11] neg_lo:[0,0,1] neg_hi:[0,0,1]
	v_pk_mul_f32 v[0:1], v[88:89], v[94:95] op_sel_hi:[0,1]
	v_pk_mul_f32 v[0:1], v[0:1], v[6:7]
	v_pk_mul_f32 v[6:7], v[88:89], v[136:137] op_sel_hi:[0,1]
	v_pk_mul_f32 v[2:3], v[6:7], v[2:3]
	v_pk_mul_f32 v[6:7], v[0:1], v[14:15]
	s_nop 0
	v_pk_fma_f32 v[6:7], v[2:3], v[46:47], v[6:7]
	v_pk_mul_f32 v[2:3], v[2:3], v[14:15]
	s_nop 0
	v_pk_fma_f32 v[14:15], v[0:1], v[46:47], v[2:3] neg_lo:[0,0,1] neg_hi:[0,0,1]
	v_cvt_pk_bf16_f32 v0, v8, v9
	v_cvt_pk_bf16_f32 v1, v10, v11
	v_cvt_pk_bf16_f32 v2, v16, v17
	v_cvt_pk_bf16_f32 v3, v14, v15
	ds_write_b128 v244, v[0:3] offset:144
	s_nop 1
	v_cvt_pk_bf16_f32 v0, v26, v27
	v_cvt_pk_bf16_f32 v1, v12, v13
	v_cvt_pk_bf16_f32 v2, v4, v5
	v_cvt_pk_bf16_f32 v3, v6, v7
	ds_write_b128 v244, v[0:3] offset:176
	v_readfirstlane_b32 s58, v82
	v_readfirstlane_b32 s59, v83
	v_mbcnt_lo_u32_b32 v0, -1, 0
	v_mbcnt_hi_u32_b32 v0, -1, v0
	v_mov_b32_e32 v1, v0
	v_mul_u32_u24_e32 v2, 0xaaab, v1
	v_lshrrev_b32_e32 v2, 22, v2
	v_mul_u32_u24_e32 v3, 0x60, v2
	v_sub_u32_e32 v3, v1, v3
	v_mul_u32_u24_e32 v4, 0x1556, v3
	v_lshrrev_b32_e32 v4, 16, v4
	v_mul_u32_u24_e32 v5, 12, v4
	v_sub_u32_e32 v5, v3, v5
	v_lshl_add_u32 v6, v4, 3, v2
	v_mul_u32_u24_e32 v6, 0xc0, v6
	v_lshl_add_u32 v6, v5, 4, v6
	v_add_u32_e32 v6, s57, v6
	ds_read_b128 v[16:19], v6
	v_mul_u32_u24_e32 v10, 0x180000, v2
	v_lshl_add_u32 v10, v3, 4, v10
	v_add_u32_e32 v1, 0x40, v0
	v_mul_u32_u24_e32 v2, 0xaaab, v1
	v_lshrrev_b32_e32 v2, 22, v2
	v_mul_u32_u24_e32 v3, 0x60, v2
	v_sub_u32_e32 v3, v1, v3
	v_mul_u32_u24_e32 v4, 0x1556, v3
	v_lshrrev_b32_e32 v4, 16, v4
	v_mul_u32_u24_e32 v5, 12, v4
	v_sub_u32_e32 v5, v3, v5
	v_lshl_add_u32 v7, v4, 3, v2
	v_mul_u32_u24_e32 v7, 0xc0, v7
	v_lshl_add_u32 v7, v5, 4, v7
	v_add_u32_e32 v7, s57, v7
	ds_read_b128 v[20:23], v7
	v_mul_u32_u24_e32 v11, 0x180000, v2
	v_lshl_add_u32 v11, v3, 4, v11
	v_add_u32_e32 v1, 0x80, v0
	v_mul_u32_u24_e32 v2, 0xaaab, v1
	v_lshrrev_b32_e32 v2, 22, v2
	v_mul_u32_u24_e32 v3, 0x60, v2
	v_sub_u32_e32 v3, v1, v3
	v_mul_u32_u24_e32 v4, 0x1556, v3
	v_lshrrev_b32_e32 v4, 16, v4
	v_mul_u32_u24_e32 v5, 12, v4
	v_sub_u32_e32 v5, v3, v5
	v_lshl_add_u32 v8, v4, 3, v2
	v_mul_u32_u24_e32 v8, 0xc0, v8
	v_lshl_add_u32 v8, v5, 4, v8
	v_add_u32_e32 v8, s57, v8
	ds_read_b128 v[24:27], v8
	v_mul_u32_u24_e32 v12, 0x180000, v2
	v_lshl_add_u32 v12, v3, 4, v12
	v_add_u32_e32 v1, 0xc0, v0
	v_mul_u32_u24_e32 v2, 0xaaab, v1
	v_lshrrev_b32_e32 v2, 22, v2
	v_mul_u32_u24_e32 v3, 0x60, v2
	v_sub_u32_e32 v3, v1, v3
	v_mul_u32_u24_e32 v4, 0x1556, v3
	v_lshrrev_b32_e32 v4, 16, v4
	v_mul_u32_u24_e32 v5, 12, v4
	v_sub_u32_e32 v5, v3, v5
	v_lshl_add_u32 v9, v4, 3, v2
	v_mul_u32_u24_e32 v9, 0xc0, v9
	v_lshl_add_u32 v9, v5, 4, v9
	v_add_u32_e32 v9, s57, v9
	ds_read_b128 v[28:31], v9
	v_mul_u32_u24_e32 v13, 0x180000, v2
	v_lshl_add_u32 v13, v3, 4, v13
	s_waitcnt lgkmcnt(0)
	global_store_dwordx4 v10, v[16:19], s[58:59]
	global_store_dwordx4 v11, v[20:23], s[58:59]
	global_store_dwordx4 v12, v[24:27], s[58:59]
	global_store_dwordx4 v13, v[28:31], s[58:59]
	v_add_u32_e32 v1, 0x100, v0
	v_mul_u32_u24_e32 v2, 0xaaab, v1
	v_lshrrev_b32_e32 v2, 22, v2
	v_mul_u32_u24_e32 v3, 0x60, v2
	v_sub_u32_e32 v3, v1, v3
	v_mul_u32_u24_e32 v4, 0x1556, v3
	v_lshrrev_b32_e32 v4, 16, v4
	v_mul_u32_u24_e32 v5, 12, v4
	v_sub_u32_e32 v5, v3, v5
	v_lshl_add_u32 v6, v4, 3, v2
	v_mul_u32_u24_e32 v6, 0xc0, v6
	v_lshl_add_u32 v6, v5, 4, v6
	v_add_u32_e32 v6, s57, v6
	ds_read_b128 v[16:19], v6
	v_mul_u32_u24_e32 v10, 0x180000, v2
	v_lshl_add_u32 v10, v3, 4, v10
	v_add_u32_e32 v1, 0x140, v0
	v_mul_u32_u24_e32 v2, 0xaaab, v1
	v_lshrrev_b32_e32 v2, 22, v2
	v_mul_u32_u24_e32 v3, 0x60, v2
	v_sub_u32_e32 v3, v1, v3
	v_mul_u32_u24_e32 v4, 0x1556, v3
	v_lshrrev_b32_e32 v4, 16, v4
	v_mul_u32_u24_e32 v5, 12, v4
	v_sub_u32_e32 v5, v3, v5
	v_lshl_add_u32 v7, v4, 3, v2
	v_mul_u32_u24_e32 v7, 0xc0, v7
	v_lshl_add_u32 v7, v5, 4, v7
	v_add_u32_e32 v7, s57, v7
	ds_read_b128 v[20:23], v7
	v_mul_u32_u24_e32 v11, 0x180000, v2
	v_lshl_add_u32 v11, v3, 4, v11
	v_add_u32_e32 v1, 0x180, v0
	v_mul_u32_u24_e32 v2, 0xaaab, v1
	v_lshrrev_b32_e32 v2, 22, v2
	v_mul_u32_u24_e32 v3, 0x60, v2
	v_sub_u32_e32 v3, v1, v3
	v_mul_u32_u24_e32 v4, 0x1556, v3
	v_lshrrev_b32_e32 v4, 16, v4
	v_mul_u32_u24_e32 v5, 12, v4
	v_sub_u32_e32 v5, v3, v5
	v_lshl_add_u32 v8, v4, 3, v2
	v_mul_u32_u24_e32 v8, 0xc0, v8
	v_lshl_add_u32 v8, v5, 4, v8
	v_add_u32_e32 v8, s57, v8
	ds_read_b128 v[24:27], v8
	v_mul_u32_u24_e32 v12, 0x180000, v2
	v_lshl_add_u32 v12, v3, 4, v12
	v_add_u32_e32 v1, 0x1c0, v0
	v_mul_u32_u24_e32 v2, 0xaaab, v1
	v_lshrrev_b32_e32 v2, 22, v2
	v_mul_u32_u24_e32 v3, 0x60, v2
	v_sub_u32_e32 v3, v1, v3
	v_mul_u32_u24_e32 v4, 0x1556, v3
	v_lshrrev_b32_e32 v4, 16, v4
	v_mul_u32_u24_e32 v5, 12, v4
	v_sub_u32_e32 v5, v3, v5
	v_lshl_add_u32 v9, v4, 3, v2
	v_mul_u32_u24_e32 v9, 0xc0, v9
	v_lshl_add_u32 v9, v5, 4, v9
	v_add_u32_e32 v9, s57, v9
	ds_read_b128 v[28:31], v9
	v_mul_u32_u24_e32 v13, 0x180000, v2
	v_lshl_add_u32 v13, v3, 4, v13
	s_waitcnt lgkmcnt(0)
	global_store_dwordx4 v10, v[16:19], s[58:59]
	global_store_dwordx4 v11, v[20:23], s[58:59]
	global_store_dwordx4 v12, v[24:27], s[58:59]
	global_store_dwordx4 v13, v[28:31], s[58:59]
	v_add_u32_e32 v1, 0x200, v0
	v_mul_u32_u24_e32 v2, 0xaaab, v1
	v_lshrrev_b32_e32 v2, 22, v2
	v_mul_u32_u24_e32 v3, 0x60, v2
	v_sub_u32_e32 v3, v1, v3
	v_mul_u32_u24_e32 v4, 0x1556, v3
	v_lshrrev_b32_e32 v4, 16, v4
	v_mul_u32_u24_e32 v5, 12, v4
	v_sub_u32_e32 v5, v3, v5
	v_lshl_add_u32 v6, v4, 3, v2
	v_mul_u32_u24_e32 v6, 0xc0, v6
	v_lshl_add_u32 v6, v5, 4, v6
	v_add_u32_e32 v6, s57, v6
	ds_read_b128 v[16:19], v6
	v_mul_u32_u24_e32 v10, 0x180000, v2
	v_lshl_add_u32 v10, v3, 4, v10
	v_add_u32_e32 v1, 0x240, v0
	v_mul_u32_u24_e32 v2, 0xaaab, v1
	v_lshrrev_b32_e32 v2, 22, v2
	v_mul_u32_u24_e32 v3, 0x60, v2
	v_sub_u32_e32 v3, v1, v3
	v_mul_u32_u24_e32 v4, 0x1556, v3
	v_lshrrev_b32_e32 v4, 16, v4
	v_mul_u32_u24_e32 v5, 12, v4
	v_sub_u32_e32 v5, v3, v5
	v_lshl_add_u32 v7, v4, 3, v2
	v_mul_u32_u24_e32 v7, 0xc0, v7
	v_lshl_add_u32 v7, v5, 4, v7
	v_add_u32_e32 v7, s57, v7
	ds_read_b128 v[20:23], v7
	v_mul_u32_u24_e32 v11, 0x180000, v2
	v_lshl_add_u32 v11, v3, 4, v11
	v_add_u32_e32 v1, 0x280, v0
	v_mul_u32_u24_e32 v2, 0xaaab, v1
	v_lshrrev_b32_e32 v2, 22, v2
	v_mul_u32_u24_e32 v3, 0x60, v2
	v_sub_u32_e32 v3, v1, v3
	v_mul_u32_u24_e32 v4, 0x1556, v3
	v_lshrrev_b32_e32 v4, 16, v4
	v_mul_u32_u24_e32 v5, 12, v4
	v_sub_u32_e32 v5, v3, v5
	v_lshl_add_u32 v8, v4, 3, v2
	v_mul_u32_u24_e32 v8, 0xc0, v8
	v_lshl_add_u32 v8, v5, 4, v8
	v_add_u32_e32 v8, s57, v8
	ds_read_b128 v[24:27], v8
	v_mul_u32_u24_e32 v12, 0x180000, v2
	v_lshl_add_u32 v12, v3, 4, v12
	v_add_u32_e32 v1, 0x2c0, v0
	v_mul_u32_u24_e32 v2, 0xaaab, v1
	v_lshrrev_b32_e32 v2, 22, v2
	v_mul_u32_u24_e32 v3, 0x60, v2
	v_sub_u32_e32 v3, v1, v3
	v_mul_u32_u24_e32 v4, 0x1556, v3
	v_lshrrev_b32_e32 v4, 16, v4
	v_mul_u32_u24_e32 v5, 12, v4
	v_sub_u32_e32 v5, v3, v5
	v_lshl_add_u32 v9, v4, 3, v2
	v_mul_u32_u24_e32 v9, 0xc0, v9
	v_lshl_add_u32 v9, v5, 4, v9
	v_add_u32_e32 v9, s57, v9
	ds_read_b128 v[28:31], v9
	v_mul_u32_u24_e32 v13, 0x180000, v2
	v_lshl_add_u32 v13, v3, 4, v13
	s_waitcnt lgkmcnt(0)
	global_store_dwordx4 v10, v[16:19], s[58:59]
	global_store_dwordx4 v11, v[20:23], s[58:59]
	global_store_dwordx4 v12, v[24:27], s[58:59]
	global_store_dwordx4 v13, v[28:31], s[58:59]
	global_load_dwordx4 v[70:73], v[64:65], off offset:16
	global_load_dwordx4 v[32:35], v[64:65], off offset:48
	global_load_dwordx4 v[74:77], v[64:65], off offset:64
	global_load_dwordx4 v[84:87], v[64:65], off
	global_load_dwordx4 v[52:55], v[64:65], off offset:32
	v_mul_f32_e32 v0, 0x4b800000, v185
	global_load_dwordx4 v[88:91], v[64:65], off offset:80
	v_cndmask_b32_e32 v0, v185, v0, vcc
	v_rsq_f32_e32 v42, v0
	global_load_dwordx4 v[16:19], v[64:65], off offset:176
	global_load_dwordx4 v[20:23], v[64:65], off offset:160
	global_load_dwordx4 v[24:27], v[64:65], off offset:144
	global_load_dwordx4 v[28:31], v[64:65], off offset:128
	global_load_dwordx4 v[56:59], v[64:65], off offset:112
	global_load_dwordx4 v[150:153], v[64:65], off offset:96
	global_load_dwordx4 v[130:133], v[40:41], off offset:16
	global_load_dwordx4 v[36:39], v[40:41], off
	global_load_dwordx4 v[0:3], v[64:65], off offset:240
	global_load_dwordx4 v[4:7], v[64:65], off offset:224
	global_load_dwordx4 v[8:11], v[64:65], off offset:208
	global_load_dwordx4 v[12:15], v[64:65], off offset:192
	global_load_dwordx4 v[60:63], v[40:41], off offset:48
	global_load_dwordx4 v[154:157], v[40:41], off offset:32
	v_mul_f32_e32 v43, 0x45800000, v42
	v_cndmask_b32_e32 v122, v42, v43, vcc
	v_mul_f32_e32 v111, v122, v122
	s_waitcnt vmcnt(19)
	v_lshlrev_b32_e32 v202, 16, v70
	v_and_b32_e32 v203, 0xffff0000, v70
	v_lshlrev_b32_e32 v200, 16, v71
	s_waitcnt vmcnt(16)
	v_and_b32_e32 v69, 0xffff0000, v86
	v_and_b32_e32 v209, 0xffff0000, v84
	v_and_b32_e32 v201, 0xffff0000, v71
	v_lshlrev_b32_e32 v68, 16, v86
	v_lshlrev_b32_e32 v70, 16, v85
	v_and_b32_e32 v71, 0xffff0000, v85
	v_lshlrev_b32_e32 v208, 16, v84
	v_mov_b32_e32 v84, v69
	v_mov_b32_e32 v85, v209
	v_lshlrev_b32_e32 v192, 16, v74
	v_and_b32_e32 v193, 0xffff0000, v74
	v_mul_f32_e32 v74, v71, v71
	v_mov_b32_e32 v78, v68
	v_mov_b32_e32 v79, v208
	v_pk_mul_f32 v[84:85], v[84:85], v[84:85]
	v_lshlrev_b32_e32 v194, 16, v75
	v_and_b32_e32 v195, 0xffff0000, v75
	v_pk_fma_f32 v[74:75], v[70:71], v[70:71], v[74:75] op_sel_hi:[1,1,0]
	v_pk_fma_f32 v[78:79], v[78:79], v[78:79], v[84:85]
	s_waitcnt vmcnt(15)
	v_and_b32_e32 v175, 0xffff0000, v52
	v_pk_add_f32 v[74:75], v[78:79], v[74:75] op_sel:[1,0] op_sel_hi:[0,1]
	v_and_b32_e32 v174, 0xffff0000, v72
	v_pk_add_f32 v[84:85], v[78:79], v[74:75]
	v_lshlrev_b32_e32 v179, 16, v52
	v_lshlrev_b32_e32 v178, 16, v72
	v_pk_mul_f32 v[74:75], v[174:175], v[174:175]
	v_lshlrev_b32_e32 v206, 16, v87
	v_and_b32_e32 v207, 0xffff0000, v87
	v_pk_fma_f32 v[86:87], v[178:179], v[178:179], v[74:75]
	v_pk_mov_b32 v[74:75], v[72:73], v[54:55] op_sel:[1,0]
	v_lshlrev_b32_e32 v185, 16, v54
	v_and_b32_e32 v177, 0xffff0000, v75
	v_and_b32_e32 v176, 0xffff0000, v74
	v_lshlrev_b32_e32 v184, 16, v73
	v_pk_mul_f32 v[72:73], v[176:177], v[176:177]
	s_waitcnt vmcnt(6)
	v_and_b32_e32 v165, 0xffff0000, v36
	v_and_b32_e32 v164, 0xffff0000, v76
	v_pk_fma_f32 v[214:215], v[184:185], v[184:185], v[72:73]
	v_lshlrev_b32_e32 v163, 16, v36
	v_lshlrev_b32_e32 v162, 16, v76
	v_pk_mul_f32 v[72:73], v[164:165], v[164:165]
	v_lshlrev_b32_e32 v159, 16, v38
	v_pk_fma_f32 v[94:95], v[162:163], v[162:163], v[72:73]
	v_pk_mov_b32 v[72:73], v[76:77], v[38:39] op_sel:[1,0]
	v_lshlrev_b32_e32 v158, 16, v77
	v_and_b32_e32 v161, 0xffff0000, v73
	v_and_b32_e32 v160, 0xffff0000, v72
	v_pk_mul_f32 v[72:73], v[160:161], v[160:161]
	v_and_b32_e32 v137, 0xffff0000, v130
	v_and_b32_e32 v136, 0xffff0000, v88
	v_and_b32_e32 v129, 0xffff0000, v131
	v_and_b32_e32 v128, 0xffff0000, v89
	v_pk_fma_f32 v[96:97], v[158:159], v[158:159], v[72:73]
	v_lshlrev_b32_e32 v135, 16, v130
	v_lshlrev_b32_e32 v134, 16, v88
	v_pk_mul_f32 v[72:73], v[136:137], v[136:137]
	v_lshlrev_b32_e32 v127, 16, v131
	v_lshlrev_b32_e32 v126, 16, v89
	v_pk_mul_f32 v[74:75], v[128:129], v[128:129]
	v_pk_fma_f32 v[72:73], v[134:135], v[134:135], v[72:73]
	v_pk_fma_f32 v[74:75], v[126:127], v[126:127], v[74:75]
	v_and_b32_e32 v143, 0xffff0000, v132
	v_and_b32_e32 v142, 0xffff0000, v90
	v_pk_add_f32 v[72:73], v[72:73], v[74:75]
	v_lshlrev_b32_e32 v141, 16, v132
	v_lshlrev_b32_e32 v140, 16, v90
	v_pk_mul_f32 v[74:75], v[142:143], v[142:143]
	v_lshlrev_b32_e32 v131, 16, v133
	v_pk_fma_f32 v[74:75], v[140:141], v[140:141], v[74:75]
	v_and_b32_e32 v133, 0xffff0000, v133
	v_and_b32_e32 v132, 0xffff0000, v91
	v_and_b32_e32 v139, 0xffff0000, v33
	v_and_b32_e32 v138, 0xffff0000, v32
	v_pk_add_f32 v[72:73], v[74:75], v[72:73]
	v_lshlrev_b32_e32 v130, 16, v91
	v_pk_mul_f32 v[74:75], v[132:133], v[132:133]
	v_lshlrev_b32_e32 v147, 16, v33
	v_lshlrev_b32_e32 v146, 16, v32
	v_pk_mul_f32 v[32:33], v[138:139], v[138:139]
	v_and_b32_e32 v145, 0xffff0000, v35
	v_and_b32_e32 v144, 0xffff0000, v34
	v_pk_fma_f32 v[74:75], v[130:131], v[130:131], v[74:75]
	s_waitcnt vmcnt(0)
	v_and_b32_e32 v191, 0xffff0000, v154
	v_and_b32_e32 v190, 0xffff0000, v150
	v_and_b32_e32 v183, 0xffff0000, v155
	v_and_b32_e32 v182, 0xffff0000, v151
	v_pk_fma_f32 v[32:33], v[146:147], v[146:147], v[32:33]
	v_lshlrev_b32_e32 v149, 16, v35
	v_lshlrev_b32_e32 v148, 16, v34
	v_pk_mul_f32 v[34:35], v[144:145], v[144:145]
	v_pk_add_f32 v[236:237], v[74:75], v[72:73]
	v_lshlrev_b32_e32 v189, 16, v154
	v_lshlrev_b32_e32 v188, 16, v150
	v_pk_mul_f32 v[72:73], v[190:191], v[190:191]
	v_lshlrev_b32_e32 v181, 16, v155
	v_lshlrev_b32_e32 v180, 16, v151
	v_pk_mul_f32 v[74:75], v[182:183], v[182:183]
	v_pk_add_f32 v[32:33], v[32:33], v[32:33] op_sel:[0,1] op_sel_hi:[1,0]
	v_pk_fma_f32 v[34:35], v[148:149], v[148:149], v[34:35]
	v_pk_fma_f32 v[72:73], v[188:189], v[188:189], v[72:73]
	v_pk_fma_f32 v[74:75], v[180:181], v[180:181], v[74:75]
	v_and_b32_e32 v199, 0xffff0000, v156
	v_and_b32_e32 v198, 0xffff0000, v152
	v_pk_add_f32 v[32:33], v[34:35], v[32:33]
	v_pk_add_f32 v[72:73], v[72:73], v[74:75]
	v_lshlrev_b32_e32 v197, 16, v156
	v_lshlrev_b32_e32 v196, 16, v152
	v_pk_mul_f32 v[74:75], v[198:199], v[198:199]
	v_mul_f32_e32 v40, v203, v203
	v_pk_add_f32 v[92:93], v[34:35], v[32:33] op_sel:[1,0] op_sel_hi:[0,1]
	v_mul_f32_e32 v32, v193, v193
	v_pk_fma_f32 v[74:75], v[196:197], v[196:197], v[74:75]
	v_and_b32_e32 v187, 0xffff0000, v157
	v_and_b32_e32 v186, 0xffff0000, v153
	v_pk_fma_f32 v[80:81], v[202:203], v[202:203], v[40:41] op_sel_hi:[1,1,0]
	v_mul_f32_e32 v40, v201, v201
	v_pk_fma_f32 v[64:65], v[192:193], v[192:193], v[32:33] op_sel_hi:[1,1,0]
	v_mul_f32_e32 v32, v195, v195
	v_pk_add_f32 v[72:73], v[74:75], v[72:73]
	v_lshlrev_b32_e32 v205, 16, v157
	v_lshlrev_b32_e32 v204, 16, v153
	v_pk_mul_f32 v[74:75], v[186:187], v[186:187]
	v_pk_fma_f32 v[82:83], v[200:201], v[200:201], v[40:41] op_sel_hi:[1,1,0]
	v_pk_fma_f32 v[66:67], v[194:195], v[194:195], v[32:33] op_sel_hi:[1,1,0]
	global_load_dwordx4 v[32:35], v101, s[46:47] offset:48
	global_load_dwordx4 v[40:43], v101, s[46:47] offset:32
	global_load_dwordx4 v[44:47], v101, s[46:47] offset:16
	global_load_dwordx4 v[48:51], v101, s[46:47]
	v_pk_fma_f32 v[74:75], v[204:205], v[204:205], v[74:75]
	v_and_b32_e32 v169, 0xffff0000, v60
	v_and_b32_e32 v168, 0xffff0000, v56
	v_and_b32_e32 v153, 0xffff0000, v61
	v_and_b32_e32 v152, 0xffff0000, v57
	v_pk_add_f32 v[238:239], v[74:75], v[72:73]
	v_lshlrev_b32_e32 v167, 16, v60
	v_lshlrev_b32_e32 v166, 16, v56
	v_pk_mul_f32 v[72:73], v[168:169], v[168:169]
	v_lshlrev_b32_e32 v151, 16, v61
	v_lshlrev_b32_e32 v150, 16, v57
	v_pk_mul_f32 v[56:57], v[152:153], v[152:153]
	v_and_b32_e32 v173, 0xffff0000, v62
	v_and_b32_e32 v172, 0xffff0000, v58
	v_pk_fma_f32 v[72:73], v[166:167], v[166:167], v[72:73]
	v_pk_fma_f32 v[56:57], v[150:151], v[150:151], v[56:57]
	v_lshlrev_b32_e32 v171, 16, v62
	v_lshlrev_b32_e32 v170, 16, v58
	v_pk_mul_f32 v[60:61], v[172:173], v[172:173]
	v_and_b32_e32 v157, 0xffff0000, v63
	v_and_b32_e32 v156, 0xffff0000, v59
	v_pk_add_f32 v[56:57], v[72:73], v[56:57]
	v_pk_fma_f32 v[60:61], v[170:171], v[170:171], v[60:61]
	v_lshlrev_b32_e32 v155, 16, v63
	v_lshlrev_b32_e32 v154, 16, v59
	v_pk_mul_f32 v[58:59], v[156:157], v[156:157]
	v_pk_add_f32 v[56:57], v[60:61], v[56:57]
	v_pk_fma_f32 v[58:59], v[154:155], v[154:155], v[58:59]
	v_mul_f32_e32 v98, v207, v207
	v_pk_add_f32 v[240:241], v[58:59], v[56:57]
	global_load_dwordx4 v[56:59], v101, s[46:47] offset:112
	global_load_dwordx4 v[60:63], v101, s[46:47] offset:96
	global_load_dwordx4 v[72:75], v101, s[46:47] offset:80
	global_load_dwordx4 v[76:79], v101, s[46:47] offset:64
	global_load_dwordx4 v[220:223], v101, s[46:47] offset:144
	global_load_dwordx4 v[224:227], v101, s[46:47] offset:128
	global_load_dwordx4 v[228:231], v101, s[46:47] offset:176
	global_load_dwordx4 v[232:235], v101, s[46:47] offset:160
	v_lshlrev_b32_e32 v210, 16, v55
	v_and_b32_e32 v55, 0xffff0000, v55
	v_lshlrev_b32_e32 v212, 16, v53
	v_and_b32_e32 v213, 0xffff0000, v53
	v_mov_b32_e32 v99, v98
	v_mov_b32_e32 v211, v55
	v_pk_mul_f32 v[52:53], v[212:213], v[212:213]
	v_and_b32_e32 v54, s0, v54
	v_pk_mov_b32 v[88:89], v[98:99], v[210:211] op_sel:[1,0]
	v_mov_b32_e32 v81, v52
	v_mov_b32_e32 v83, v53
	v_pk_mul_f32 v[54:55], v[54:55], v[54:55]
	v_pk_fma_f32 v[90:91], v[206:207], v[206:207], v[88:89]
	v_pk_mul_f32 v[88:89], v[210:211], v[88:89] op_sel_hi:[0,1]
	v_pk_add_f32 v[52:53], v[80:81], v[82:83]
	v_mov_b32_e32 v91, v89
	v_mov_b32_e32 v85, v55
	v_pk_add_f32 v[52:53], v[86:87], v[52:53]
	v_lshlrev_b32_e32 v216, 16, v37
	v_and_b32_e32 v217, 0xffff0000, v37
	v_pk_add_f32 v[54:55], v[90:91], v[84:85]
	v_pk_add_f32 v[52:53], v[214:215], v[52:53]
	v_pk_mul_f32 v[36:37], v[216:217], v[216:217]
	v_pk_add_f32 v[52:53], v[54:55], v[52:53]
	v_lshlrev_b32_e32 v214, 16, v39
	v_and_b32_e32 v215, 0xffff0000, v39
	v_mov_b32_e32 v65, v36
	v_mov_b32_e32 v67, v37
	v_pk_add_f32 v[98:99], v[52:53], v[52:53] op_sel:[0,1] op_sel_hi:[1,0]
	v_pk_mul_f32 v[38:39], v[214:215], v[214:215]
	v_pk_add_f32 v[36:37], v[64:65], v[66:67]
	v_mov_b32_e32 v93, v39
	v_mov_b32_e32 v99, v38
	v_pk_add_f32 v[36:37], v[94:95], v[36:37]
	v_pk_add_f32 v[38:39], v[98:99], v[92:93]
	v_pk_add_f32 v[36:37], v[96:97], v[36:37]
	v_mov_b32_e32 v246, v162
	v_pk_add_f32 v[36:37], v[38:39], v[36:37]
	v_mov_b32_e32 v242, v178
	v_pk_add_f32 v[36:37], v[36:37], v[236:237]
	v_mov_b32_e32 v243, v174
	v_pk_add_f32 v[36:37], v[36:37], v[238:239]
	v_mov_b32_e32 v244, v184
	v_pk_add_f32 v[36:37], v[36:37], v[240:241]
	v_mov_b32_e32 v245, v176
	v_fmac_f32_e32 v37, v111, v36
	v_fmamk_f32 v36, v37, 0x3c2aaaab, v100
	v_mul_f32_e32 v37, 0x4b800000, v36
	v_cmp_gt_f32_e32 vcc, s19, v36
	global_load_dwordx4 v[52:55], v101, s[46:47] offset:240
	global_load_dwordx4 v[80:83], v101, s[46:47] offset:224
	global_load_dwordx4 v[84:87], v101, s[46:47] offset:208
	global_load_dwordx4 v[88:91], v101, s[46:47] offset:192
	v_cndmask_b32_e32 v36, v36, v37, vcc
	v_rsq_f32_e32 v111, v36
	global_load_dwordx4 v[36:39], v101, s[46:47] offset:304
	global_load_dwordx4 v[64:67], v101, s[46:47] offset:288
	global_load_dwordx4 v[96:99], v101, s[46:47] offset:256
	global_load_dwordx4 v[92:95], v101, s[46:47] offset:272
	v_mov_b32_e32 v247, v164
	v_mov_b32_e32 v240, v126
	v_mul_f32_e32 v123, 0x45800000, v111
	v_cndmask_b32_e32 v162, v111, v123, vcc
	v_mul_f32_e32 v178, v122, v162
	s_waitcnt vmcnt(18)
	v_pk_mul_f32 v[40:41], v[40:41], v[178:179] op_sel_hi:[1,0]
	v_pk_mul_f32 v[32:33], v[32:33], v[178:179] op_sel_hi:[1,0]
	v_pk_mul_f32 v[40:41], v[40:41], v[202:203]
	v_pk_mul_f32 v[202:203], v[32:33], v[242:243]
	v_pk_mul_f32 v[32:33], v[42:43], v[178:179] op_sel_hi:[1,0]
	s_waitcnt vmcnt(16)
	v_pk_mul_f32 v[48:49], v[48:49], v[178:179] op_sel_hi:[1,0]
	v_pk_mul_f32 v[200:201], v[32:33], v[200:201]
	v_pk_mul_f32 v[32:33], v[34:35], v[178:179] op_sel_hi:[1,0]
	v_pk_mul_f32 v[208:209], v[48:49], v[208:209]
	v_pk_mul_f32 v[44:45], v[44:45], v[178:179] op_sel_hi:[1,0]
	v_pk_mul_f32 v[48:49], v[50:51], v[178:179] op_sel_hi:[1,0]
	v_pk_mul_f32 v[46:47], v[46:47], v[178:179] op_sel_hi:[1,0]
	v_pk_mul_f32 v[244:245], v[32:33], v[244:245]
	v_pk_mul_f32 v[44:45], v[44:45], v[68:69]
	v_pk_mul_f32 v[236:237], v[48:49], v[70:71]
	v_pk_mul_f32 v[46:47], v[46:47], v[206:207]
	v_cvt_pk_bf16_f32 v32, v40, v41
	v_cvt_pk_bf16_f32 v33, v200, v201
	v_cvt_pk_bf16_f32 v34, v202, v203
	v_cvt_pk_bf16_f32 v35, v244, v245
	global_load_dwordx4 v[48:51], v101, s[46:47] offset:368
	global_load_dwordx4 v[68:71], v101, s[46:47] offset:352
	v_cvt_pk_bf16_f32 v206, v208, v209
	v_cvt_pk_bf16_f32 v207, v236, v237
	v_cvt_pk_bf16_f32 v208, v44, v45
	v_cvt_pk_bf16_f32 v209, v46, v47
	global_load_dwordx4 v[236:239], v101, s[46:47] offset:320
	global_load_dwordx4 v[44:47], v101, s[46:47] offset:336
	s_waitcnt vmcnt(14)
	v_pk_mul_f32 v[40:41], v[226:227], v[178:179] op_sel_hi:[1,0]
	s_mul_i32 s57, s33, 0xc0
	v_mbcnt_lo_u32_b32 v244, -1, 0
	v_mbcnt_hi_u32_b32 v244, -1, v244
	v_mul_u32_u24_e32 v244, 0xc0, v244
	v_add_u32_e32 v244, s57, v244
	ds_write_b128 v244, v[32:35] offset:16
	ds_write_b128 v244, v[206:209]
	v_pk_mul_f32 v[40:41], v[40:41], v[194:195]
	v_pk_mul_f32 v[32:33], v[224:225], v[178:179] op_sel_hi:[1,0]
	v_mov_b32_e32 v206, v158
	v_mov_b32_e32 v207, v160
	v_pk_mul_f32 v[32:33], v[32:33], v[192:193]
	v_pk_mul_f32 v[34:35], v[220:221], v[178:179] op_sel_hi:[1,0]
	v_pk_mul_f32 v[192:193], v[222:223], v[178:179] op_sel_hi:[1,0]
	v_pk_mul_f32 v[34:35], v[34:35], v[246:247]
	v_pk_mul_f32 v[192:193], v[192:193], v[206:207]
	v_cvt_pk_bf16_f32 v32, v32, v33
	v_cvt_pk_bf16_f32 v33, v40, v41
	v_cvt_pk_bf16_f32 v34, v34, v35
	v_cvt_pk_bf16_f32 v35, v192, v193
	v_mov_b32_e32 v42, v140
	v_mov_b32_e32 v43, v142
	ds_write_b128 v244, v[32:35] offset:64
	v_mov_b32_e32 v208, v134
	v_mov_b32_e32 v209, v136
	s_waitcnt vmcnt(13)
	v_pk_mul_f32 v[34:35], v[178:179], v[228:229] op_sel_hi:[0,1]
	v_mov_b32_e32 v241, v128
	v_mov_b32_e32 v242, v130
	v_mov_b32_e32 v243, v132
	s_waitcnt vmcnt(12)
	v_pk_mul_f32 v[32:33], v[178:179], v[232:233] op_sel_hi:[0,1]
	v_pk_mul_f32 v[34:35], v[34:35], v[42:43]
	v_pk_mul_f32 v[40:41], v[178:179], v[234:235] op_sel_hi:[0,1]
	v_pk_mul_f32 v[42:43], v[178:179], v[230:231] op_sel_hi:[0,1]
	v_pk_mul_f32 v[32:33], v[32:33], v[208:209]
	v_pk_mul_f32 v[40:41], v[40:41], v[240:241]
	v_pk_mul_f32 v[42:43], v[42:43], v[242:243]
	v_cvt_pk_bf16_f32 v32, v32, v33
	v_cvt_pk_bf16_f32 v33, v40, v41
	v_cvt_pk_bf16_f32 v34, v34, v35
	v_cvt_pk_bf16_f32 v35, v42, v43
	global_load_dwordx4 v[40:43], v[120:121], off
	global_load_dwordx4 v[192:195], v[118:119], off
	v_mov_b32_e32 v176, v185
	ds_write_b128 v244, v[32:35] offset:80
	global_load_dwordx4 v[32:35], v[118:119], off offset:16
	s_nop 0
	global_load_dwordx4 v[200:203], v[120:121], off offset:16
	v_mov_b32_e32 v174, v179
	v_pk_mul_f32 v[76:77], v[76:77], v[178:179] op_sel_hi:[1,0]
	v_pk_mul_f32 v[72:73], v[72:73], v[178:179] op_sel_hi:[1,0]
	v_pk_mul_f32 v[76:77], v[76:77], v[174:175]
	v_pk_mul_f32 v[174:175], v[72:73], v[176:177]
	v_pk_mul_f32 v[72:73], v[78:79], v[178:179] op_sel_hi:[1,0]
	v_mov_b32_e32 v206, v148
	v_pk_mul_f32 v[78:79], v[72:73], v[212:213]
	v_pk_mul_f32 v[72:73], v[74:75], v[178:179] op_sel_hi:[1,0]
	v_mov_b32_e32 v207, v144
	v_pk_mul_f32 v[176:177], v[72:73], v[210:211]
	v_cvt_pk_bf16_f32 v72, v76, v77
	v_cvt_pk_bf16_f32 v73, v78, v79
	v_cvt_pk_bf16_f32 v74, v174, v175
	v_cvt_pk_bf16_f32 v75, v176, v177
	v_pk_mul_f32 v[56:57], v[56:57], v[178:179] op_sel_hi:[1,0]
	v_mov_b32_e32 v185, v138
	v_mov_b32_e32 v138, v147
	ds_write_b128 v244, v[72:75] offset:32
	v_mov_b32_e32 v184, v146
	v_mov_b32_e32 v144, v149
	v_pk_mul_f32 v[72:73], v[56:57], v[206:207]
	v_pk_mul_f32 v[56:57], v[62:63], v[178:179] op_sel_hi:[1,0]
	v_pk_mul_f32 v[60:61], v[60:61], v[178:179] op_sel_hi:[1,0]
	v_pk_mul_f32 v[62:63], v[56:57], v[138:139]
	v_pk_mul_f32 v[56:57], v[58:59], v[178:179] op_sel_hi:[1,0]
	v_pk_mul_f32 v[60:61], v[60:61], v[184:185]
	v_pk_mul_f32 v[74:75], v[56:57], v[144:145]
	v_cvt_pk_bf16_f32 v56, v60, v61
	v_cvt_pk_bf16_f32 v57, v62, v63
	v_cvt_pk_bf16_f32 v58, v72, v73
	v_cvt_pk_bf16_f32 v59, v74, v75
	v_mov_b32_e32 v146, v188
	v_mov_b32_e32 v147, v190
	v_mov_b32_e32 v148, v196
	v_mov_b32_e32 v149, v198
	v_mov_b32_e32 v208, v180
	v_mov_b32_e32 v209, v182
	v_mov_b32_e32 v220, v204
	v_mov_b32_e32 v221, v186
	ds_write_b128 v244, v[56:59] offset:48
	s_waitcnt vmcnt(12)
	v_pk_mul_f32 v[60:61], v[178:179], v[90:91] op_sel_hi:[0,1]
	v_pk_mul_f32 v[62:63], v[178:179], v[86:87] op_sel_hi:[0,1]
	v_pk_mul_f32 v[56:57], v[178:179], v[88:89] op_sel_hi:[0,1]
	v_pk_mul_f32 v[58:59], v[178:179], v[84:85] op_sel_hi:[0,1]
	v_pk_mul_f32 v[56:57], v[56:57], v[146:147]
	v_pk_mul_f32 v[58:59], v[58:59], v[148:149]
	v_pk_mul_f32 v[60:61], v[60:61], v[208:209]
	v_pk_mul_f32 v[62:63], v[62:63], v[220:221]
	v_cvt_pk_bf16_f32 v56, v56, v57
	v_cvt_pk_bf16_f32 v57, v60, v61
	v_cvt_pk_bf16_f32 v58, v58, v59
	v_cvt_pk_bf16_f32 v59, v62, v63
	v_mov_b32_e32 v198, v197
	ds_write_b128 v244, v[56:59] offset:96
	v_mov_b32_e32 v160, v159
	v_mov_b32_e32 v182, v181
	v_pk_mul_f32 v[58:59], v[162:163], v[198:199] op_sel_hi:[0,1]
	s_waitcnt vmcnt(4)
	v_pk_mul_f32 v[76:77], v[58:59], v[44:45]
	v_pk_mul_f32 v[44:45], v[162:163], v[160:161] op_sel_hi:[0,1]
	v_pk_mul_f32 v[78:79], v[44:45], v[92:93]
	v_mov_b32_e32 v224, v170
	v_mov_b32_e32 v225, v172
	v_pk_mul_f32 v[56:57], v[178:179], v[80:81] op_sel_hi:[0,1]
	v_pk_mul_f32 v[52:53], v[178:179], v[52:53] op_sel_hi:[0,1]
	v_mov_b32_e32 v222, v166
	v_mov_b32_e32 v223, v168
	v_pk_mul_f32 v[62:63], v[52:53], v[224:225]
	v_pk_mul_f32 v[52:53], v[178:179], v[82:83] op_sel_hi:[0,1]
	v_mov_b32_e32 v164, v163
	v_mov_b32_e32 v186, v205
	v_pk_mul_f32 v[60:61], v[56:57], v[222:223]
	v_pk_mul_f32 v[56:57], v[162:163], v[164:165] op_sel_hi:[0,1]
	v_mov_b32_e32 v190, v189
	v_pk_mul_f32 v[72:73], v[56:57], v[96:97]
	v_pk_mul_f32 v[56:57], v[162:163], v[190:191] op_sel_hi:[0,1]
	v_pk_mul_f32 v[74:75], v[56:57], v[236:237]
	s_waitcnt vmcnt(3)
	v_pk_mul_f32 v[56:57], v[72:73], v[40:41]
	v_mov_b32_e32 v226, v150
	s_waitcnt vmcnt(0)
	v_pk_mul_f32 v[44:45], v[78:79], v[200:201]
	v_pk_fma_f32 v[56:57], v[74:75], v[192:193], v[56:57]
	v_pk_fma_f32 v[58:59], v[76:77], v[32:33], v[44:45]
	v_pk_mul_f32 v[44:45], v[162:163], v[216:217] op_sel_hi:[0,1]
	v_pk_mul_f32 v[80:81], v[44:45], v[98:99]
	v_pk_mul_f32 v[44:45], v[162:163], v[182:183] op_sel_hi:[0,1]
	v_pk_mul_f32 v[82:83], v[44:45], v[238:239]
	v_pk_mul_f32 v[44:45], v[80:81], v[42:43]
	v_mov_b32_e32 v227, v152
	v_pk_fma_f32 v[84:85], v[82:83], v[194:195], v[44:45]
	v_pk_mul_f32 v[44:45], v[162:163], v[214:215] op_sel_hi:[0,1]
	v_pk_mul_f32 v[86:87], v[44:45], v[94:95]
	v_pk_mul_f32 v[44:45], v[162:163], v[186:187] op_sel_hi:[0,1]
	v_pk_mul_f32 v[88:89], v[44:45], v[46:47]
	v_pk_mul_f32 v[44:45], v[86:87], v[202:203]
	v_cvt_pk_bf16_f32 v46, v58, v59
	v_pk_fma_f32 v[90:91], v[88:89], v[34:35], v[44:45]
	v_cvt_pk_bf16_f32 v44, v56, v57
	v_cvt_pk_bf16_f32 v45, v84, v85
	v_cvt_pk_bf16_f32 v47, v90, v91
	ds_write_b128 v244, v[44:47] offset:160
	v_mov_b32_e32 v228, v154
	v_mov_b32_e32 v229, v156
	global_load_dwordx4 v[44:47], v[120:121], off offset:32
	global_load_dwordx4 v[56:59], v[118:119], off offset:32
	v_pk_mul_f32 v[84:85], v[52:53], v[226:227]
	v_pk_mul_f32 v[52:53], v[178:179], v[54:55] op_sel_hi:[0,1]
	v_pk_mul_f32 v[90:91], v[52:53], v[228:229]
	v_cvt_pk_bf16_f32 v52, v60, v61
	v_cvt_pk_bf16_f32 v53, v84, v85
	v_cvt_pk_bf16_f32 v54, v62, v63
	v_cvt_pk_bf16_f32 v55, v90, v91
	ds_write_b128 v244, v[52:55] offset:112
	global_load_dwordx4 v[52:55], v[120:121], off offset:48
	s_nop 0
	global_load_dwordx4 v[60:63], v[118:119], off offset:48
	v_pk_mul_f32 v[40:41], v[74:75], v[40:41]
	v_mov_b32_e32 v136, v135
	v_pk_fma_f32 v[40:41], v[72:73], v[192:193], v[40:41] neg_lo:[0,0,1] neg_hi:[0,0,1]
	v_pk_mul_f32 v[72:73], v[76:77], v[200:201]
	v_mov_b32_e32 v168, v167
	v_pk_fma_f32 v[72:73], v[78:79], v[32:33], v[72:73] neg_lo:[0,0,1] neg_hi:[0,0,1]
	v_pk_mul_f32 v[32:33], v[82:83], v[42:43]
	v_mov_b32_e32 v172, v171
	v_pk_fma_f32 v[42:43], v[80:81], v[194:195], v[32:33] neg_lo:[0,0,1] neg_hi:[0,0,1]
	v_pk_mul_f32 v[32:33], v[88:89], v[202:203]
	v_mov_b32_e32 v142, v141
	v_pk_fma_f32 v[74:75], v[86:87], v[34:35], v[32:33] neg_lo:[0,0,1] neg_hi:[0,0,1]
	v_cvt_pk_bf16_f32 v32, v40, v41
	v_cvt_pk_bf16_f32 v33, v42, v43
	v_cvt_pk_bf16_f32 v34, v72, v73
	v_cvt_pk_bf16_f32 v35, v74, v75
	ds_write_b128 v244, v[32:35] offset:128
	v_pk_mul_f32 v[42:43], v[162:163], v[142:143] op_sel_hi:[0,1]
	v_pk_mul_f32 v[36:37], v[42:43], v[36:37]
	v_pk_mul_f32 v[32:33], v[162:163], v[136:137] op_sel_hi:[0,1]
	v_pk_mul_f32 v[32:33], v[32:33], v[64:65]
	v_pk_mul_f32 v[34:35], v[162:163], v[168:169] op_sel_hi:[0,1]
	v_pk_mul_f32 v[34:35], v[34:35], v[68:69]
	v_mov_b32_e32 v128, v127
	v_mov_b32_e32 v152, v151
	v_mov_b32_e32 v132, v131
	v_mov_b32_e32 v156, v155
	s_waitcnt vmcnt(3)
	v_pk_mul_f32 v[40:41], v[32:33], v[44:45]
	s_waitcnt vmcnt(2)
	v_pk_fma_f32 v[40:41], v[34:35], v[56:57], v[40:41]
	v_pk_mul_f32 v[34:35], v[34:35], v[44:45]
	v_pk_mul_f32 v[44:45], v[162:163], v[152:153] op_sel_hi:[0,1]
	v_pk_fma_f32 v[32:33], v[32:33], v[56:57], v[34:35] neg_lo:[0,0,1] neg_hi:[0,0,1]
	v_pk_mul_f32 v[34:35], v[162:163], v[172:173] op_sel_hi:[0,1]
	v_pk_mul_f32 v[34:35], v[34:35], v[48:49]
	v_pk_mul_f32 v[44:45], v[44:45], v[70:71]
	v_cvt_pk_bf16_f32 v32, v32, v33
	s_waitcnt vmcnt(1)
	v_pk_mul_f32 v[42:43], v[34:35], v[52:53]
	s_waitcnt vmcnt(0)
	v_pk_fma_f32 v[42:43], v[36:37], v[60:61], v[42:43] neg_lo:[0,0,1] neg_hi:[0,0,1]
	v_pk_mul_f32 v[36:37], v[36:37], v[52:53]
	s_nop 0
	v_pk_fma_f32 v[36:37], v[34:35], v[60:61], v[36:37]
	v_pk_mul_f32 v[34:35], v[162:163], v[128:129] op_sel_hi:[0,1]
	v_pk_mul_f32 v[34:35], v[34:35], v[66:67]
	s_nop 0
	v_pk_mul_f32 v[48:49], v[34:35], v[46:47]
	s_nop 0
	v_pk_fma_f32 v[48:49], v[44:45], v[58:59], v[48:49]
	v_pk_mul_f32 v[44:45], v[44:45], v[46:47]
	s_nop 0
	v_pk_fma_f32 v[34:35], v[34:35], v[58:59], v[44:45] neg_lo:[0,0,1] neg_hi:[0,0,1]
	v_pk_mul_f32 v[44:45], v[162:163], v[132:133] op_sel_hi:[0,1]
	v_pk_mul_f32 v[38:39], v[44:45], v[38:39]
	v_pk_mul_f32 v[44:45], v[162:163], v[156:157] op_sel_hi:[0,1]
	v_pk_mul_f32 v[44:45], v[44:45], v[50:51]
	v_pk_mul_f32 v[46:47], v[38:39], v[54:55]
	v_cvt_pk_bf16_f32 v33, v34, v35
	v_pk_fma_f32 v[46:47], v[44:45], v[62:63], v[46:47]
	v_pk_mul_f32 v[44:45], v[44:45], v[54:55]
	v_cvt_pk_bf16_f32 v34, v42, v43
	v_pk_fma_f32 v[38:39], v[38:39], v[62:63], v[44:45] neg_lo:[0,0,1] neg_hi:[0,0,1]
	s_nop 0
	v_cvt_pk_bf16_f32 v35, v38, v39
	ds_write_b128 v244, v[32:35] offset:144
	s_nop 1
	v_cvt_pk_bf16_f32 v32, v40, v41
	v_cvt_pk_bf16_f32 v33, v48, v49
	v_cvt_pk_bf16_f32 v34, v36, v37
	v_cvt_pk_bf16_f32 v35, v46, v47
	ds_write_b128 v244, v[32:35] offset:176
	v_readfirstlane_b32 s60, v124
	v_readfirstlane_b32 s61, v125
	v_mbcnt_lo_u32_b32 v42, -1, 0
	v_mbcnt_hi_u32_b32 v42, -1, v42
	v_mov_b32_e32 v43, v42
	v_mul_u32_u24_e32 v44, 0xaaab, v43
	v_lshrrev_b32_e32 v44, 22, v44
	v_mul_u32_u24_e32 v45, 0x60, v44
	v_sub_u32_e32 v45, v43, v45
	v_mul_u32_u24_e32 v46, 0x1556, v45
	v_lshrrev_b32_e32 v46, 16, v46
	v_mul_u32_u24_e32 v47, 12, v46
	v_sub_u32_e32 v47, v45, v47
	v_lshl_add_u32 v48, v46, 3, v44
	v_mul_u32_u24_e32 v48, 0xc0, v48
	v_lshl_add_u32 v48, v47, 4, v48
	v_add_u32_e32 v48, s57, v48
	ds_read_b128 v[60:63], v48
	v_mul_u32_u24_e32 v52, 0x180000, v44
	v_lshl_add_u32 v52, v45, 4, v52
	v_add_u32_e32 v43, 0x40, v42
	v_mul_u32_u24_e32 v44, 0xaaab, v43
	v_lshrrev_b32_e32 v44, 22, v44
	v_mul_u32_u24_e32 v45, 0x60, v44
	v_sub_u32_e32 v45, v43, v45
	v_mul_u32_u24_e32 v46, 0x1556, v45
	v_lshrrev_b32_e32 v46, 16, v46
	v_mul_u32_u24_e32 v47, 12, v46
	v_sub_u32_e32 v47, v45, v47
	v_lshl_add_u32 v49, v46, 3, v44
	v_mul_u32_u24_e32 v49, 0xc0, v49
	v_lshl_add_u32 v49, v47, 4, v49
	v_add_u32_e32 v49, s57, v49
	ds_read_b128 v[64:67], v49
	v_mul_u32_u24_e32 v53, 0x180000, v44
	v_lshl_add_u32 v53, v45, 4, v53
	v_add_u32_e32 v43, 0x80, v42
	v_mul_u32_u24_e32 v44, 0xaaab, v43
	v_lshrrev_b32_e32 v44, 22, v44
	v_mul_u32_u24_e32 v45, 0x60, v44
	v_sub_u32_e32 v45, v43, v45
	v_mul_u32_u24_e32 v46, 0x1556, v45
	v_lshrrev_b32_e32 v46, 16, v46
	v_mul_u32_u24_e32 v47, 12, v46
	v_sub_u32_e32 v47, v45, v47
	v_lshl_add_u32 v50, v46, 3, v44
	v_mul_u32_u24_e32 v50, 0xc0, v50
	v_lshl_add_u32 v50, v47, 4, v50
	v_add_u32_e32 v50, s57, v50
	ds_read_b128 v[68:71], v50
	v_mul_u32_u24_e32 v54, 0x180000, v44
	v_lshl_add_u32 v54, v45, 4, v54
	v_add_u32_e32 v43, 0xc0, v42
	v_mul_u32_u24_e32 v44, 0xaaab, v43
	v_lshrrev_b32_e32 v44, 22, v44
	v_mul_u32_u24_e32 v45, 0x60, v44
	v_sub_u32_e32 v45, v43, v45
	v_mul_u32_u24_e32 v46, 0x1556, v45
	v_lshrrev_b32_e32 v46, 16, v46
	v_mul_u32_u24_e32 v47, 12, v46
	v_sub_u32_e32 v47, v45, v47
	v_lshl_add_u32 v51, v46, 3, v44
	v_mul_u32_u24_e32 v51, 0xc0, v51
	v_lshl_add_u32 v51, v47, 4, v51
	v_add_u32_e32 v51, s57, v51
	ds_read_b128 v[72:75], v51
	v_mul_u32_u24_e32 v55, 0x180000, v44
	v_lshl_add_u32 v55, v45, 4, v55
	s_waitcnt lgkmcnt(0)
	global_store_dwordx4 v52, v[60:63], s[60:61]
	global_store_dwordx4 v53, v[64:67], s[60:61]
	global_store_dwordx4 v54, v[68:71], s[60:61]
	global_store_dwordx4 v55, v[72:75], s[60:61]
	v_add_u32_e32 v43, 0x100, v42
	v_mul_u32_u24_e32 v44, 0xaaab, v43
	v_lshrrev_b32_e32 v44, 22, v44
	v_mul_u32_u24_e32 v45, 0x60, v44
	v_sub_u32_e32 v45, v43, v45
	v_mul_u32_u24_e32 v46, 0x1556, v45
	v_lshrrev_b32_e32 v46, 16, v46
	v_mul_u32_u24_e32 v47, 12, v46
	v_sub_u32_e32 v47, v45, v47
	v_lshl_add_u32 v48, v46, 3, v44
	v_mul_u32_u24_e32 v48, 0xc0, v48
	v_lshl_add_u32 v48, v47, 4, v48
	v_add_u32_e32 v48, s57, v48
	ds_read_b128 v[60:63], v48
	v_mul_u32_u24_e32 v52, 0x180000, v44
	v_lshl_add_u32 v52, v45, 4, v52
	v_add_u32_e32 v43, 0x140, v42
	v_mul_u32_u24_e32 v44, 0xaaab, v43
	v_lshrrev_b32_e32 v44, 22, v44
	v_mul_u32_u24_e32 v45, 0x60, v44
	v_sub_u32_e32 v45, v43, v45
	v_mul_u32_u24_e32 v46, 0x1556, v45
	v_lshrrev_b32_e32 v46, 16, v46
	v_mul_u32_u24_e32 v47, 12, v46
	v_sub_u32_e32 v47, v45, v47
	v_lshl_add_u32 v49, v46, 3, v44
	v_mul_u32_u24_e32 v49, 0xc0, v49
	v_lshl_add_u32 v49, v47, 4, v49
	v_add_u32_e32 v49, s57, v49
	ds_read_b128 v[64:67], v49
	v_mul_u32_u24_e32 v53, 0x180000, v44
	v_lshl_add_u32 v53, v45, 4, v53
	v_add_u32_e32 v43, 0x180, v42
	v_mul_u32_u24_e32 v44, 0xaaab, v43
	v_lshrrev_b32_e32 v44, 22, v44
	v_mul_u32_u24_e32 v45, 0x60, v44
	v_sub_u32_e32 v45, v43, v45
	v_mul_u32_u24_e32 v46, 0x1556, v45
	v_lshrrev_b32_e32 v46, 16, v46
	v_mul_u32_u24_e32 v47, 12, v46
	v_sub_u32_e32 v47, v45, v47
	v_lshl_add_u32 v50, v46, 3, v44
	v_mul_u32_u24_e32 v50, 0xc0, v50
	v_lshl_add_u32 v50, v47, 4, v50
	v_add_u32_e32 v50, s57, v50
	ds_read_b128 v[68:71], v50
	v_mul_u32_u24_e32 v54, 0x180000, v44
	v_lshl_add_u32 v54, v45, 4, v54
	v_add_u32_e32 v43, 0x1c0, v42
	v_mul_u32_u24_e32 v44, 0xaaab, v43
	v_lshrrev_b32_e32 v44, 22, v44
	v_mul_u32_u24_e32 v45, 0x60, v44
	v_sub_u32_e32 v45, v43, v45
	v_mul_u32_u24_e32 v46, 0x1556, v45
	v_lshrrev_b32_e32 v46, 16, v46
	v_mul_u32_u24_e32 v47, 12, v46
	v_sub_u32_e32 v47, v45, v47
	v_lshl_add_u32 v51, v46, 3, v44
	v_mul_u32_u24_e32 v51, 0xc0, v51
	v_lshl_add_u32 v51, v47, 4, v51
	v_add_u32_e32 v51, s57, v51
	ds_read_b128 v[72:75], v51
	v_mul_u32_u24_e32 v55, 0x180000, v44
	v_lshl_add_u32 v55, v45, 4, v55
	s_waitcnt lgkmcnt(0)
	global_store_dwordx4 v52, v[60:63], s[60:61]
	global_store_dwordx4 v53, v[64:67], s[60:61]
	global_store_dwordx4 v54, v[68:71], s[60:61]
	global_store_dwordx4 v55, v[72:75], s[60:61]
	v_add_u32_e32 v43, 0x200, v42
	v_mul_u32_u24_e32 v44, 0xaaab, v43
	v_lshrrev_b32_e32 v44, 22, v44
	v_mul_u32_u24_e32 v45, 0x60, v44
	v_sub_u32_e32 v45, v43, v45
	v_mul_u32_u24_e32 v46, 0x1556, v45
	v_lshrrev_b32_e32 v46, 16, v46
	v_mul_u32_u24_e32 v47, 12, v46
	v_sub_u32_e32 v47, v45, v47
	v_lshl_add_u32 v48, v46, 3, v44
	v_mul_u32_u24_e32 v48, 0xc0, v48
	v_lshl_add_u32 v48, v47, 4, v48
	v_add_u32_e32 v48, s57, v48
	ds_read_b128 v[60:63], v48
	v_mul_u32_u24_e32 v52, 0x180000, v44
	v_lshl_add_u32 v52, v45, 4, v52
	v_add_u32_e32 v43, 0x240, v42
	v_mul_u32_u24_e32 v44, 0xaaab, v43
	v_lshrrev_b32_e32 v44, 22, v44
	v_mul_u32_u24_e32 v45, 0x60, v44
	v_sub_u32_e32 v45, v43, v45
	v_mul_u32_u24_e32 v46, 0x1556, v45
	v_lshrrev_b32_e32 v46, 16, v46
	v_mul_u32_u24_e32 v47, 12, v46
	v_sub_u32_e32 v47, v45, v47
	v_lshl_add_u32 v49, v46, 3, v44
	v_mul_u32_u24_e32 v49, 0xc0, v49
	v_lshl_add_u32 v49, v47, 4, v49
	v_add_u32_e32 v49, s57, v49
	ds_read_b128 v[64:67], v49
	v_mul_u32_u24_e32 v53, 0x180000, v44
	v_lshl_add_u32 v53, v45, 4, v53
	v_add_u32_e32 v43, 0x280, v42
	v_mul_u32_u24_e32 v44, 0xaaab, v43
	v_lshrrev_b32_e32 v44, 22, v44
	v_mul_u32_u24_e32 v45, 0x60, v44
	v_sub_u32_e32 v45, v43, v45
	v_mul_u32_u24_e32 v46, 0x1556, v45
	v_lshrrev_b32_e32 v46, 16, v46
	v_mul_u32_u24_e32 v47, 12, v46
	v_sub_u32_e32 v47, v45, v47
	v_lshl_add_u32 v50, v46, 3, v44
	v_mul_u32_u24_e32 v50, 0xc0, v50
	v_lshl_add_u32 v50, v47, 4, v50
	v_add_u32_e32 v50, s57, v50
	ds_read_b128 v[68:71], v50
	v_mul_u32_u24_e32 v54, 0x180000, v44
	v_lshl_add_u32 v54, v45, 4, v54
	v_add_u32_e32 v43, 0x2c0, v42
	v_mul_u32_u24_e32 v44, 0xaaab, v43
	v_lshrrev_b32_e32 v44, 22, v44
	v_mul_u32_u24_e32 v45, 0x60, v44
	v_sub_u32_e32 v45, v43, v45
	v_mul_u32_u24_e32 v46, 0x1556, v45
	v_lshrrev_b32_e32 v46, 16, v46
	v_mul_u32_u24_e32 v47, 12, v46
	v_sub_u32_e32 v47, v45, v47
	v_lshl_add_u32 v51, v46, 3, v44
	v_mul_u32_u24_e32 v51, 0xc0, v51
	v_lshl_add_u32 v51, v47, 4, v51
	v_add_u32_e32 v51, s57, v51
	ds_read_b128 v[72:75], v51
	v_mul_u32_u24_e32 v55, 0x180000, v44
	v_lshl_add_u32 v55, v45, 4, v55
	s_waitcnt lgkmcnt(0)
	global_store_dwordx4 v52, v[60:63], s[60:61]
	global_store_dwordx4 v53, v[64:67], s[60:61]
	global_store_dwordx4 v54, v[68:71], s[60:61]
	global_store_dwordx4 v55, v[72:75], s[60:61]
	s_nop 1
	v_lshlrev_b32_e32 v34, 16, v28
	v_and_b32_e32 v35, 0xffff0000, v28
	v_lshlrev_b32_e32 v28, 16, v29
	v_and_b32_e32 v29, 0xffff0000, v29
	v_pk_mul_f32 v[36:37], v[122:123], v[28:29] op_sel_hi:[0,1]
	v_lshlrev_b32_e32 v28, 16, v30
	v_and_b32_e32 v29, 0xffff0000, v30
	v_pk_mul_f32 v[38:39], v[122:123], v[28:29] op_sel_hi:[0,1]
	v_lshlrev_b32_e32 v28, 16, v31
	v_and_b32_e32 v29, 0xffff0000, v31
	v_lshlrev_b64 v[32:33], 7, v[116:117]
	v_pk_mul_f32 v[34:35], v[122:123], v[34:35] op_sel_hi:[0,1]
	v_pk_mul_f32 v[40:41], v[122:123], v[28:29] op_sel_hi:[0,1]
	v_lshl_add_u64 v[32:33], s[12:13], 0, v[32:33]
	v_cvt_pk_bf16_f32 v28, v34, v35
	v_cvt_pk_bf16_f32 v29, v36, v37
	v_cvt_pk_bf16_f32 v30, v38, v39
	v_cvt_pk_bf16_f32 v31, v40, v41
	s_mul_i32 s57, s33, 0xc0
	v_mbcnt_lo_u32_b32 v38, -1, 0
	v_mbcnt_hi_u32_b32 v38, -1, v38
	v_mul_u32_u24_e32 v38, 0x80, v38
	v_add_u32_e32 v38, s57, v38
	ds_write_b128 v38, v[28:31]
	s_nop 1
	v_lshlrev_b32_e32 v28, 16, v24
	v_and_b32_e32 v29, 0xffff0000, v24
	v_lshlrev_b32_e32 v24, 16, v25
	v_and_b32_e32 v25, 0xffff0000, v25
	v_pk_mul_f32 v[30:31], v[122:123], v[24:25] op_sel_hi:[0,1]
	v_lshlrev_b32_e32 v24, 16, v26
	v_and_b32_e32 v25, 0xffff0000, v26
	v_pk_mul_f32 v[34:35], v[122:123], v[24:25] op_sel_hi:[0,1]
	v_lshlrev_b32_e32 v24, 16, v27
	v_and_b32_e32 v25, 0xffff0000, v27
	v_pk_mul_f32 v[28:29], v[122:123], v[28:29] op_sel_hi:[0,1]
	v_pk_mul_f32 v[36:37], v[122:123], v[24:25] op_sel_hi:[0,1]
	v_cvt_pk_bf16_f32 v24, v28, v29
	v_cvt_pk_bf16_f32 v25, v30, v31
	v_cvt_pk_bf16_f32 v26, v34, v35
	v_cvt_pk_bf16_f32 v27, v36, v37
	ds_write_b128 v38, v[24:27] offset:16
	s_nop 1
	v_lshlrev_b32_e32 v24, 16, v20
	v_and_b32_e32 v25, 0xffff0000, v20
	v_lshlrev_b32_e32 v20, 16, v21
	v_and_b32_e32 v21, 0xffff0000, v21
	v_pk_mul_f32 v[26:27], v[122:123], v[20:21] op_sel_hi:[0,1]
	v_lshlrev_b32_e32 v20, 16, v22
	v_and_b32_e32 v21, 0xffff0000, v22
	v_pk_mul_f32 v[28:29], v[122:123], v[20:21] op_sel_hi:[0,1]
	v_lshlrev_b32_e32 v20, 16, v23
	v_and_b32_e32 v21, 0xffff0000, v23
	v_pk_mul_f32 v[24:25], v[122:123], v[24:25] op_sel_hi:[0,1]
	v_pk_mul_f32 v[30:31], v[122:123], v[20:21] op_sel_hi:[0,1]
	v_cvt_pk_bf16_f32 v20, v24, v25
	v_cvt_pk_bf16_f32 v21, v26, v27
	v_cvt_pk_bf16_f32 v22, v28, v29
	v_cvt_pk_bf16_f32 v23, v30, v31
	ds_write_b128 v38, v[20:23] offset:32
	s_nop 1
	v_lshlrev_b32_e32 v20, 16, v16
	v_and_b32_e32 v21, 0xffff0000, v16
	v_lshlrev_b32_e32 v16, 16, v17
	v_and_b32_e32 v17, 0xffff0000, v17
	v_pk_mul_f32 v[22:23], v[122:123], v[16:17] op_sel_hi:[0,1]
	v_lshlrev_b32_e32 v16, 16, v18
	v_and_b32_e32 v17, 0xffff0000, v18
	v_pk_mul_f32 v[24:25], v[122:123], v[16:17] op_sel_hi:[0,1]
	v_lshlrev_b32_e32 v16, 16, v19
	v_and_b32_e32 v17, 0xffff0000, v19
	v_pk_mul_f32 v[20:21], v[122:123], v[20:21] op_sel_hi:[0,1]
	v_pk_mul_f32 v[26:27], v[122:123], v[16:17] op_sel_hi:[0,1]
	v_cvt_pk_bf16_f32 v16, v20, v21
	v_cvt_pk_bf16_f32 v17, v22, v23
	v_cvt_pk_bf16_f32 v18, v24, v25
	v_cvt_pk_bf16_f32 v19, v26, v27
	ds_write_b128 v38, v[16:19] offset:48
	s_nop 1
	v_lshlrev_b32_e32 v16, 16, v12
	v_and_b32_e32 v17, 0xffff0000, v12
	v_lshlrev_b32_e32 v12, 16, v13
	v_and_b32_e32 v13, 0xffff0000, v13
	v_pk_mul_f32 v[18:19], v[122:123], v[12:13] op_sel_hi:[0,1]
	v_lshlrev_b32_e32 v12, 16, v14
	v_and_b32_e32 v13, 0xffff0000, v14
	v_pk_mul_f32 v[20:21], v[122:123], v[12:13] op_sel_hi:[0,1]
	v_lshlrev_b32_e32 v12, 16, v15
	v_and_b32_e32 v13, 0xffff0000, v15
	v_pk_mul_f32 v[16:17], v[122:123], v[16:17] op_sel_hi:[0,1]
	v_pk_mul_f32 v[22:23], v[122:123], v[12:13] op_sel_hi:[0,1]
	v_cvt_pk_bf16_f32 v12, v16, v17
	v_cvt_pk_bf16_f32 v13, v18, v19
	v_cvt_pk_bf16_f32 v14, v20, v21
	v_cvt_pk_bf16_f32 v15, v22, v23
	ds_write_b128 v38, v[12:15] offset:64
	s_nop 1
	v_lshlrev_b32_e32 v12, 16, v8
	v_and_b32_e32 v13, 0xffff0000, v8
	v_lshlrev_b32_e32 v8, 16, v9
	v_and_b32_e32 v9, 0xffff0000, v9
	v_pk_mul_f32 v[14:15], v[122:123], v[8:9] op_sel_hi:[0,1]
	v_lshlrev_b32_e32 v8, 16, v10
	v_and_b32_e32 v9, 0xffff0000, v10
	v_pk_mul_f32 v[16:17], v[122:123], v[8:9] op_sel_hi:[0,1]
	v_lshlrev_b32_e32 v8, 16, v11
	v_and_b32_e32 v9, 0xffff0000, v11
	v_pk_mul_f32 v[12:13], v[122:123], v[12:13] op_sel_hi:[0,1]
	v_pk_mul_f32 v[18:19], v[122:123], v[8:9] op_sel_hi:[0,1]
	v_cvt_pk_bf16_f32 v8, v12, v13
	v_cvt_pk_bf16_f32 v9, v14, v15
	v_cvt_pk_bf16_f32 v10, v16, v17
	v_cvt_pk_bf16_f32 v11, v18, v19
	ds_write_b128 v38, v[8:11] offset:80
	s_nop 1
	v_lshlrev_b32_e32 v8, 16, v4
	v_and_b32_e32 v9, 0xffff0000, v4
	v_lshlrev_b32_e32 v4, 16, v5
	v_and_b32_e32 v5, 0xffff0000, v5
	v_pk_mul_f32 v[10:11], v[122:123], v[4:5] op_sel_hi:[0,1]
	v_lshlrev_b32_e32 v4, 16, v6
	v_and_b32_e32 v5, 0xffff0000, v6
	v_pk_mul_f32 v[12:13], v[122:123], v[4:5] op_sel_hi:[0,1]
	v_lshlrev_b32_e32 v4, 16, v7
	v_and_b32_e32 v5, 0xffff0000, v7
	v_pk_mul_f32 v[8:9], v[122:123], v[8:9] op_sel_hi:[0,1]
	v_pk_mul_f32 v[14:15], v[122:123], v[4:5] op_sel_hi:[0,1]
	v_cvt_pk_bf16_f32 v4, v8, v9
	v_cvt_pk_bf16_f32 v5, v10, v11
	v_cvt_pk_bf16_f32 v6, v12, v13
	v_cvt_pk_bf16_f32 v7, v14, v15
	ds_write_b128 v38, v[4:7] offset:96
	s_nop 1
	v_lshlrev_b32_e32 v4, 16, v0
	v_and_b32_e32 v5, 0xffff0000, v0
	v_lshlrev_b32_e32 v0, 16, v1
	v_and_b32_e32 v1, 0xffff0000, v1
	v_pk_mul_f32 v[6:7], v[122:123], v[0:1] op_sel_hi:[0,1]
	v_lshlrev_b32_e32 v0, 16, v2
	v_and_b32_e32 v1, 0xffff0000, v2
	v_pk_mul_f32 v[8:9], v[122:123], v[0:1] op_sel_hi:[0,1]
	v_lshlrev_b32_e32 v0, 16, v3
	v_and_b32_e32 v1, 0xffff0000, v3
	v_pk_mul_f32 v[4:5], v[122:123], v[4:5] op_sel_hi:[0,1]
	v_pk_mul_f32 v[10:11], v[122:123], v[0:1] op_sel_hi:[0,1]
	v_cvt_pk_bf16_f32 v0, v4, v5
	v_cvt_pk_bf16_f32 v1, v6, v7
	v_cvt_pk_bf16_f32 v2, v8, v9
	v_cvt_pk_bf16_f32 v3, v10, v11
	ds_write_b128 v38, v[0:3] offset:112
	v_readfirstlane_b32 s64, v32
	v_readfirstlane_b32 s65, v33
	v_mbcnt_lo_u32_b32 v34, -1, 0
	v_mbcnt_hi_u32_b32 v34, -1, v34
	v_and_b32_e32 v35, 56, v34
	v_lshlrev_b32_e32 v35, 7, v35
	v_and_b32_e32 v36, 7, v34
	v_lshl_add_u32 v35, v36, 4, v35
	v_add_u32_e32 v35, s57, v35
	v_lshlrev_b32_e32 v37, 4, v34
	ds_read_b128 v[50:53], v35
	ds_read_b128 v[54:57], v35 offset:128
	ds_read_b128 v[58:61], v35 offset:256
	ds_read_b128 v[62:65], v35 offset:384
	s_waitcnt lgkmcnt(0)
	global_store_dwordx4 v37, v[50:53], s[64:65]
	s_add_u32 s64, s64, 0x100000
	s_addc_u32 s65, s65, 0
	global_store_dwordx4 v37, v[54:57], s[64:65]
	s_add_u32 s64, s64, 0x100000
	s_addc_u32 s65, s65, 0
	global_store_dwordx4 v37, v[58:61], s[64:65]
	s_add_u32 s64, s64, 0x100000
	s_addc_u32 s65, s65, 0
	global_store_dwordx4 v37, v[62:65], s[64:65]
	s_add_u32 s64, s64, 0x100000
	s_addc_u32 s65, s65, 0
	ds_read_b128 v[50:53], v35 offset:512
	ds_read_b128 v[54:57], v35 offset:640
	ds_read_b128 v[58:61], v35 offset:768
	ds_read_b128 v[62:65], v35 offset:896
	s_waitcnt lgkmcnt(0)
	global_store_dwordx4 v37, v[50:53], s[64:65]
	s_add_u32 s64, s64, 0x100000
	s_addc_u32 s65, s65, 0
	global_store_dwordx4 v37, v[54:57], s[64:65]
	s_add_u32 s64, s64, 0x100000
	s_addc_u32 s65, s65, 0
	global_store_dwordx4 v37, v[58:61], s[64:65]
	s_add_u32 s64, s64, 0x100000
	s_addc_u32 s65, s65, 0
	global_store_dwordx4 v37, v[62:65], s[64:65]
	s_add_u32 s64, s64, 0x100000
	s_addc_u32 s65, s65, 0
	s_cbranch_scc1 .LBB0_535
